# write-through (sc1) stores for all outputs of the three GEMM phases so the grid barrier write-back finds a clean L2
# baseline (speedup 1.0000x reference)
; __device__ __forceinline__ unsigned cvt_pk_bf16(float lo, float hi) { unsigned r; asm volatile("v_cvt_pk_bf16_f32 %0, %1, %2" : "=v"(r) : "v"(lo), "v"(hi)); return r; }
;     __device__ __forceinline__ void operator()(const f32x4 (&acc)[2][2][4][2], const Unit& u, int wr, int wc, int fr, int fq) const {
;     ...
;             for (int m = 0; m < 4; ++m) { bf16_t* rowp = O + (size_t)(row0 + ai * HALF + m * 16) * ldc + col0;
; #pragma unroll
;                 for (int bj = 0; bj < 2; ++bj) { const f32x4 v0 = acc[ai][bj][m][0], v1 = acc[ai][bj][m][1];
;                     u32x4 w; w.x = cvt_pk_bf16(v0[0], v0[1]); w.y = cvt_pk_bf16(v0[2], v0[3]); w.z = cvt_pk_bf16(v1[0], v1[1]); w.w = cvt_pk_bf16(v1[2], v1[3]);
;                     *(u32x4*)(rowp + bj * HALF) = w; } }
.LBB0_172:
	v_lshl_or_b32 v146, s73, 8, v152
	v_lshl_add_u32 v158, s20, 8, v150
	v_ashrrev_i32_e32 v147, 31, v146
	v_mov_b64_e32 v[144:145], s[54:55]
	v_mad_i64_i32 v[156:157], s[22:23], v158, s72, v[144:145]
	v_lshlrev_b64 v[146:147], 1, v[146:147]
	v_lshl_add_u64 v[156:157], v[156:157], 0, v[146:147]
	v_cvt_pk_bf16_f32 v124, v124, v125
	v_cvt_pk_bf16_f32 v125, v126, v127
	v_cvt_pk_bf16_f32 v126, v120, v121
	v_cvt_pk_bf16_f32 v127, v122, v123
	global_store_dwordx4 v[156:157], v[124:127], off sc1
	v_cvt_pk_bf16_f32 v112, v112, v113
	v_cvt_pk_bf16_f32 v113, v114, v115
	v_cvt_pk_bf16_f32 v114, v104, v105
	v_or_b32_e32 v104, 16, v158
	v_mad_i64_i32 v[104:105], s[22:23], v104, s72, v[144:145]
	v_cvt_pk_bf16_f32 v115, v106, v107
	global_store_dwordx4 v[156:157], v[112:115], off offset:256 sc1
	s_andn2_b64 vcc, exec, s[0:1]
	s_mov_b64 s[0:1], -1
	v_lshl_add_u64 v[112:113], v[104:105], 0, v[146:147]
	v_cvt_pk_bf16_f32 v104, v116, v117
	v_cvt_pk_bf16_f32 v105, v118, v119
	v_cvt_pk_bf16_f32 v106, v108, v109
	v_cvt_pk_bf16_f32 v107, v110, v111
	global_store_dwordx4 v[112:113], v[104:107], off sc1
	v_cvt_pk_bf16_f32 v96, v96, v97
	v_cvt_pk_bf16_f32 v97, v98, v99
	v_cvt_pk_bf16_f32 v98, v88, v89
	v_or_b32_e32 v88, 32, v158
	v_mad_i64_i32 v[88:89], s[22:23], v88, s72, v[144:145]
	v_cvt_pk_bf16_f32 v99, v90, v91
	global_store_dwordx4 v[112:113], v[96:99], off offset:256 sc1
	s_nop 1
	v_lshl_add_u64 v[96:97], v[88:89], 0, v[146:147]
	v_cvt_pk_bf16_f32 v88, v100, v101
	v_cvt_pk_bf16_f32 v89, v102, v103
	v_cvt_pk_bf16_f32 v90, v92, v93
	v_cvt_pk_bf16_f32 v91, v94, v95
	global_store_dwordx4 v[96:97], v[88:91], off sc1
	v_cvt_pk_bf16_f32 v80, v80, v81
	v_cvt_pk_bf16_f32 v81, v82, v83
	v_cvt_pk_bf16_f32 v82, v72, v73
	v_or_b32_e32 v72, 48, v158
	v_mad_i64_i32 v[72:73], s[22:23], v72, s72, v[144:145]
	v_cvt_pk_bf16_f32 v83, v74, v75
	global_store_dwordx4 v[96:97], v[80:83], off offset:256 sc1
	s_nop 1
	v_lshl_add_u64 v[80:81], v[72:73], 0, v[146:147]
	v_cvt_pk_bf16_f32 v72, v84, v85
	v_cvt_pk_bf16_f32 v73, v86, v87
	v_cvt_pk_bf16_f32 v74, v76, v77
	v_cvt_pk_bf16_f32 v75, v78, v79
	global_store_dwordx4 v[80:81], v[72:75], off sc1
	v_cvt_pk_bf16_f32 v68, v68, v69
	v_cvt_pk_bf16_f32 v69, v70, v71
	v_cvt_pk_bf16_f32 v70, v64, v65
	v_add_u32_e32 v64, 0x80, v158
	v_mad_i64_i32 v[64:65], s[22:23], v64, s72, v[144:145]
	v_lshl_add_u64 v[64:65], v[64:65], 0, v[146:147]
	v_cvt_pk_bf16_f32 v71, v66, v67
	global_store_dwordx4 v[80:81], v[68:71], off offset:256 sc1
	v_cvt_pk_bf16_f32 v60, v60, v61
	v_cvt_pk_bf16_f32 v61, v62, v63
	v_cvt_pk_bf16_f32 v62, v56, v57
	v_cvt_pk_bf16_f32 v63, v58, v59
	global_store_dwordx4 v[64:65], v[60:63], off sc1
	v_cvt_pk_bf16_f32 v48, v48, v49
	v_cvt_pk_bf16_f32 v49, v50, v51
	v_cvt_pk_bf16_f32 v50, v40, v41
	v_add_u32_e32 v40, 0x90, v158
	v_mad_i64_i32 v[40:41], s[22:23], v40, s72, v[144:145]
	v_cvt_pk_bf16_f32 v51, v42, v43
	global_store_dwordx4 v[64:65], v[48:51], off offset:256 sc1
	s_nop 1
	v_lshl_add_u64 v[48:49], v[40:41], 0, v[146:147]
	v_cvt_pk_bf16_f32 v40, v52, v53
	v_cvt_pk_bf16_f32 v41, v54, v55
	v_cvt_pk_bf16_f32 v42, v44, v45
	v_cvt_pk_bf16_f32 v43, v46, v47
	global_store_dwordx4 v[48:49], v[40:43], off sc1
	v_cvt_pk_bf16_f32 v32, v32, v33
	v_cvt_pk_bf16_f32 v33, v34, v35
	v_cvt_pk_bf16_f32 v34, v24, v25
	v_add_u32_e32 v24, 0xa0, v158
	v_mad_i64_i32 v[24:25], s[22:23], v24, s72, v[144:145]
	v_cvt_pk_bf16_f32 v35, v26, v27
	global_store_dwordx4 v[48:49], v[32:35], off offset:256 sc1
	s_nop 1
	v_lshl_add_u64 v[32:33], v[24:25], 0, v[146:147]
	v_cvt_pk_bf16_f32 v24, v36, v37
	v_cvt_pk_bf16_f32 v25, v38, v39
	v_cvt_pk_bf16_f32 v26, v28, v29
	v_cvt_pk_bf16_f32 v27, v30, v31
	global_store_dwordx4 v[32:33], v[24:27], off sc1
	v_cvt_pk_bf16_f32 v16, v16, v17
	v_cvt_pk_bf16_f32 v17, v18, v19
	v_cvt_pk_bf16_f32 v18, v8, v9
	v_add_u32_e32 v8, 0xb0, v158
	v_mad_i64_i32 v[8:9], s[22:23], v8, s72, v[144:145]
	v_cvt_pk_bf16_f32 v19, v10, v11
	global_store_dwordx4 v[32:33], v[16:19], off offset:256 sc1
	s_nop 1
	v_lshl_add_u64 v[16:17], v[8:9], 0, v[146:147]
	v_cvt_pk_bf16_f32 v8, v20, v21
	v_cvt_pk_bf16_f32 v9, v22, v23
	v_cvt_pk_bf16_f32 v10, v12, v13
	v_cvt_pk_bf16_f32 v11, v14, v15
	global_store_dwordx4 v[16:17], v[8:11], off sc1
	v_cvt_pk_bf16_f32 v4, v4, v5
	v_cvt_pk_bf16_f32 v5, v6, v7
	v_cvt_pk_bf16_f32 v6, v0, v1
	v_cvt_pk_bf16_f32 v7, v2, v3
	global_store_dwordx4 v[16:17], v[4:7], off offset:256 sc1
	s_cbranch_vccnz .LBB0_165
	s_andn2_b64 vcc, exec, s[4:5]
	s_cbranch_vccnz .LBB0_164
	s_barrier
	s_branch .LBB0_164

; __device__ __forceinline__ void quantise_tables(const Args& A, int gw, int NGW, int row_lo, int row_hi) {
;     ...
;     for (int row = row_lo + gw; row < row_hi; row += 4 * NGW) {
;         f32x4 v[4][4]; int rr[4];
; #pragma unroll
;         for (int q = 0; q < 4; ++q) { const int r = row + q * NGW; rr[q] = r; const int rc = r < row_hi ? r : row;
;             const float* s = (rc < 16384 ? A.pu + (size_t)rc * 1024 : A.pv + (size_t)(rc - 16384) * 1024) + 16 * lane;
; #pragma unroll
;             for (int j = 0; j < 4; ++j) v[q][j] = *(const f32x4*)(s + 4 * j); }
; #pragma unroll
;         for (int q = 0; q < 4; ++q) {
;             float mx = 0.f;
; #pragma unroll
;             for (int j = 0; j < 4; ++j)
; #pragma unroll
;                 for (int e = 0; e < 4; ++e) mx = fmaxf(mx, fabsf(v[q][j][e]));
;             mx = xrow_max(mx);
;             mx = fmaxf(mx, __int_as_float(__builtin_amdgcn_mov_dpp(__float_as_int(mx), 0xB1, 0xF, 0xF, true)));
;             mx = fmaxf(mx, __int_as_float(__builtin_amdgcn_mov_dpp(__float_as_int(mx), 0x4E, 0xF, 0xF, true)));
;             mx = fmaxf(mx, __int_as_float(__builtin_amdgcn_mov_dpp(__float_as_int(mx), 0x141, 0xF, 0xF, true)));
;             mx = fmaxf(mx, __int_as_float(__builtin_amdgcn_mov_dpp(__float_as_int(mx), 0x140, 0xF, 0xF, true)));
;             const float sc = fmaxf(mx, 1e-30f) * (1.f / 256.f), inv = 1.f / sc;
;             u32x4 o4;
; #pragma unroll
;             for (int j = 0; j < 4; ++j) { int w0 = __builtin_amdgcn_cvt_pk_fp8_f32(v[q][j][0] * inv, v[q][j][1] * inv, 0, false); w0 = __builtin_amdgcn_cvt_pk_fp8_f32(v[q][j][2] * inv, v[q][j][3] * inv, w0, true); o4[j] = (unsigned)w0; }
;             if (rr[q] < row_hi) { *(u32x4*)(T8 + (size_t)rr[q] * 1024 + 16 * lane) = o4; if (lane == 0) SC[rr[q]] = sc; }
.LBB0_180:
	v_add_u32_e32 v60, s21, v62
	v_ashrrev_i32_e32 v61, 31, v60
	v_lshlrev_b64 v[0:1], 12, v[60:61]
	v_lshl_add_u64 v[0:1], v[52:53], 0, v[0:1]
	global_load_dwordx4 v[68:71], v[0:1], off
	global_load_dwordx4 v[72:75], v[0:1], off offset:16
	global_load_dwordx4 v[76:79], v[0:1], off offset:32
	global_load_dwordx4 v[80:83], v[0:1], off offset:48
	v_add_u32_e32 v58, v63, v62
	v_add_u32_e32 v56, s23, v62
	v_cmp_gt_i32_e64 s[8:9], s20, v58
	v_add_u32_e32 v54, s24, v62
	v_cmp_gt_i32_e64 s[6:7], s20, v56
	v_cndmask_b32_e64 v0, v60, v58, s[8:9]
	v_cmp_gt_i32_e64 s[4:5], s20, v54
	v_cndmask_b32_e64 v4, v60, v56, s[6:7]
	v_ashrrev_i32_e32 v1, 31, v0
	v_add_u32_e32 v2, 0xffffc000, v0
	v_cmp_gt_i32_e32 vcc, s20, v0
	v_cndmask_b32_e64 v8, v60, v54, s[4:5]
	v_ashrrev_i32_e32 v5, 31, v4
	v_add_u32_e32 v6, 0xffffc000, v4
	v_cndmask_b32_e32 v1, 0, v1, vcc
	v_cndmask_b32_e32 v0, v2, v0, vcc
	v_cndmask_b32_e32 v3, v64, v65, vcc
	v_cndmask_b32_e32 v2, v66, v67, vcc
	v_cmp_gt_i32_e32 vcc, s20, v4
	v_ashrrev_i32_e32 v9, 31, v8
	v_add_u32_e32 v10, 0xffffc000, v8
	v_cndmask_b32_e32 v5, 0, v5, vcc
	v_cndmask_b32_e32 v4, v6, v4, vcc
	v_cndmask_b32_e32 v7, v64, v65, vcc
	v_cndmask_b32_e32 v6, v66, v67, vcc
	v_cmp_gt_i32_e32 vcc, s20, v8
	v_lshlrev_b64 v[0:1], 12, v[0:1]
	v_lshlrev_b64 v[4:5], 12, v[4:5]
	v_cndmask_b32_e32 v9, 0, v9, vcc
	v_cndmask_b32_e32 v8, v10, v8, vcc
	v_cndmask_b32_e32 v11, v64, v65, vcc
	v_cndmask_b32_e32 v10, v66, v67, vcc
	v_lshlrev_b64 v[8:9], 12, v[8:9]
	v_lshl_add_u64 v[0:1], v[2:3], 0, v[0:1]
	v_lshl_add_u64 v[2:3], v[6:7], 0, v[4:5]
	v_lshl_add_u64 v[4:5], v[10:11], 0, v[8:9]
	v_lshl_add_u64 v[0:1], v[0:1], 0, v[48:49]
	v_lshl_add_u64 v[2:3], v[2:3], 0, v[48:49]
	v_lshl_add_u64 v[12:13], v[4:5], 0, v[48:49]
	global_load_dwordx4 v[32:35], v[0:1], off offset:48
	global_load_dwordx4 v[36:39], v[0:1], off offset:32
	global_load_dwordx4 v[40:43], v[0:1], off offset:16
	global_load_dwordx4 v[44:47], v[0:1], off
	global_load_dwordx4 v[16:19], v[2:3], off offset:48
	global_load_dwordx4 v[20:23], v[2:3], off offset:32
	global_load_dwordx4 v[24:27], v[2:3], off offset:16
	global_load_dwordx4 v[28:31], v[2:3], off
	s_nop 0
	global_load_dwordx4 v[0:3], v[12:13], off offset:48
	global_load_dwordx4 v[4:7], v[12:13], off offset:32
	global_load_dwordx4 v[8:11], v[12:13], off offset:16
	s_nop 0
	global_load_dwordx4 v[12:15], v[12:13], off
	v_mov_b32_e32 v84, 0
	v_mov_b32_e32 v85, 0
	v_mov_b32_e32 v86, 0
	v_mov_b32_e32 v87, 0
	s_waitcnt vmcnt(15)
	v_max3_f32 v55, |v68|, 0, |v69|
	v_max3_f32 v55, v55, |v70|, |v71|
	s_waitcnt vmcnt(14)
	v_max3_f32 v55, v55, |v72|, |v73|
	v_max3_f32 v55, v55, |v74|, |v75|
	s_waitcnt vmcnt(13)
	v_max3_f32 v55, v55, |v76|, |v77|
	v_max3_f32 v55, v55, |v78|, |v79|
	s_waitcnt vmcnt(12)
	v_max3_f32 v55, v55, |v80|, |v81|
	v_max3_f32 v55, v55, |v82|, |v83|
	v_mov_b32_e32 v57, v55
	s_nop 1
	v_permlane16_swap_b32_e32 v55, v57
	v_max_f32_e32 v57, v57, v57
	v_max_f32_e32 v55, v55, v55
	v_max_f32_e32 v55, v55, v57
	v_mov_b32_e32 v57, v55
	s_nop 1
	v_permlane32_swap_b32_e32 v55, v57
	v_max_f32_e32 v57, v57, v57
	v_max_f32_e32 v55, v55, v55
	v_max_f32_e32 v55, v55, v57
	s_nop 1
	v_mov_b32_dpp v57, v55 quad_perm:[1,0,3,2] row_mask:0xf bank_mask:0xf bound_ctrl:1
	v_max_f32_e32 v57, v57, v57
	v_max_f32_e32 v55, v55, v57
	s_nop 1
	v_mov_b32_dpp v57, v55 quad_perm:[2,3,0,1] row_mask:0xf bank_mask:0xf bound_ctrl:1
	v_max_f32_e32 v57, v57, v57
	v_max_f32_e32 v55, v55, v57
	s_nop 1
	v_mov_b32_dpp v57, v55 row_half_mirror row_mask:0xf bank_mask:0xf bound_ctrl:1
	v_max_f32_e32 v57, v57, v57
	v_max_f32_e32 v55, v55, v57
	s_nop 1
	v_mov_b32_dpp v57, v55 row_mirror row_mask:0xf bank_mask:0xf bound_ctrl:1
	v_max3_f32 v55, v55, v57, s25
	v_mul_f32_e32 v55, 0x3b800000, v55
	v_div_scale_f32 v57, s[16:17], v55, v55, 1.0
	v_rcp_f32_e32 v59, v57
	v_div_scale_f32 v88, vcc, 1.0, v55, 1.0
	v_fma_f32 v89, -v57, v59, 1.0
	v_fmac_f32_e32 v59, v89, v59
	v_mul_f32_e32 v89, v88, v59
	v_fma_f32 v90, -v57, v89, v88
	v_fmac_f32_e32 v89, v90, v59
	v_fma_f32 v57, -v57, v89, v88
	v_div_fmas_f32 v57, v57, v59, v89
	v_div_fixup_f32 v57, v57, v55, 1.0
	v_mul_f32_e32 v68, v68, v57
	v_mul_f32_e32 v69, v69, v57
	v_mul_f32_e32 v72, v72, v57
	v_mul_f32_e32 v73, v73, v57
	v_mul_f32_e32 v76, v76, v57
	v_mul_f32_e32 v77, v77, v57
	v_mul_f32_e32 v80, v80, v57
	v_mul_f32_e32 v81, v81, v57
	v_cvt_pk_fp8_f32 v84, v68, v69
	v_cvt_pk_fp8_f32 v85, v72, v73
	v_cvt_pk_fp8_f32 v86, v76, v77
	v_cvt_pk_fp8_f32 v87, v80, v81
	v_mul_f32_e32 v59, v70, v57
	v_mul_f32_e32 v70, v71, v57
	v_mul_f32_e32 v71, v74, v57
	v_mul_f32_e32 v74, v75, v57
	v_mul_f32_e32 v75, v78, v57
	v_mul_f32_e32 v78, v79, v57
	v_mul_f32_e32 v79, v82, v57
	v_mul_f32_e32 v57, v83, v57
	v_cvt_pk_fp8_f32 v84, v59, v70 op_sel:[0,0,1]
	v_cvt_pk_fp8_f32 v85, v71, v74 op_sel:[0,0,1]
	v_cvt_pk_fp8_f32 v86, v75, v78 op_sel:[0,0,1]
	v_cvt_pk_fp8_f32 v87, v79, v57 op_sel:[0,0,1]
	v_lshlrev_b64 v[68:69], 10, v[60:61]
	v_lshl_add_u64 v[68:69], v[50:51], 0, v[68:69]
	global_store_dwordx4 v[68:69], v[84:87], off sc1
	s_and_saveexec_b64 s[16:17], s[0:1]
	s_cbranch_execz .LBB0_182
	v_lshl_add_u64 v[60:61], v[60:61], 3, s[12:13]
	global_store_dword v[60:61], v55, off sc1
; __device__ __forceinline__ void quantise_tables(const Args& A, int gw, int NGW, int row_lo, int row_hi) {
;     ...
;         for (int q = 0; q < 4; ++q) {
;             float mx = 0.f;
; #pragma unroll
;             for (int j = 0; j < 4; ++j)
; #pragma unroll
;                 for (int e = 0; e < 4; ++e) mx = fmaxf(mx, fabsf(v[q][j][e]));
;             mx = xrow_max(mx);
;             mx = fmaxf(mx, __int_as_float(__builtin_amdgcn_mov_dpp(__float_as_int(mx), 0xB1, 0xF, 0xF, true)));
;             mx = fmaxf(mx, __int_as_float(__builtin_amdgcn_mov_dpp(__float_as_int(mx), 0x4E, 0xF, 0xF, true)));
;             mx = fmaxf(mx, __int_as_float(__builtin_amdgcn_mov_dpp(__float_as_int(mx), 0x141, 0xF, 0xF, true)));
;             mx = fmaxf(mx, __int_as_float(__builtin_amdgcn_mov_dpp(__float_as_int(mx), 0x140, 0xF, 0xF, true)));
;             const float sc = fmaxf(mx, 1e-30f) * (1.f / 256.f), inv = 1.f / sc;
;             u32x4 o4;
; #pragma unroll
;             for (int j = 0; j < 4; ++j) { int w0 = __builtin_amdgcn_cvt_pk_fp8_f32(v[q][j][0] * inv, v[q][j][1] * inv, 0, false); w0 = __builtin_amdgcn_cvt_pk_fp8_f32(v[q][j][2] * inv, v[q][j][3] * inv, w0, true); o4[j] = (unsigned)w0; }
;             if (rr[q] < row_hi) { *(u32x4*)(T8 + (size_t)rr[q] * 1024 + 16 * lane) = o4; if (lane == 0) SC[rr[q]] = sc; }
.LBB0_182:
	s_or_b64 exec, exec, s[16:17]
	s_waitcnt vmcnt(9)
	v_max3_f32 v55, |v44|, 0, |v45|
	v_max3_f32 v55, v55, |v46|, |v47|
	v_max3_f32 v55, v55, |v40|, |v41|
	v_max3_f32 v55, v55, |v42|, |v43|
	v_max3_f32 v55, v55, |v36|, |v37|
	v_max3_f32 v55, v55, |v38|, |v39|
	v_max3_f32 v55, v55, |v32|, |v33|
	v_max3_f32 v55, v55, |v34|, |v35|
	v_mov_b32_e32 v57, v55
	s_nop 1
	v_permlane16_swap_b32_e32 v55, v57
	v_max_f32_e32 v57, v57, v57
	v_max_f32_e32 v55, v55, v55
	v_max_f32_e32 v55, v55, v57
	v_mov_b32_e32 v57, v55
	s_nop 1
	v_permlane32_swap_b32_e32 v55, v57
	v_max_f32_e32 v57, v57, v57
	v_max_f32_e32 v55, v55, v55
	v_max_f32_e32 v55, v55, v57
	s_nop 1
	v_mov_b32_dpp v57, v55 quad_perm:[1,0,3,2] row_mask:0xf bank_mask:0xf bound_ctrl:1
	v_max_f32_e32 v57, v57, v57
	v_max_f32_e32 v55, v55, v57
	s_nop 1
	v_mov_b32_dpp v57, v55 quad_perm:[2,3,0,1] row_mask:0xf bank_mask:0xf bound_ctrl:1
	v_max_f32_e32 v57, v57, v57
	v_max_f32_e32 v55, v55, v57
	s_nop 1
	v_mov_b32_dpp v57, v55 row_half_mirror row_mask:0xf bank_mask:0xf bound_ctrl:1
	v_max_f32_e32 v57, v57, v57
	v_max_f32_e32 v55, v55, v57
	s_nop 1
	v_mov_b32_dpp v57, v55 row_mirror row_mask:0xf bank_mask:0xf bound_ctrl:1
	s_and_saveexec_b64 s[16:17], s[8:9]
	s_cbranch_execz .LBB0_185
	v_max3_f32 v55, v55, v57, s25
	v_mul_f32_e32 v55, 0x3b800000, v55
	v_div_scale_f32 v57, s[8:9], v55, v55, 1.0
	v_rcp_f32_e32 v59, v57
	v_div_scale_f32 v60, vcc, 1.0, v55, 1.0
	v_fma_f32 v61, -v57, v59, 1.0
	v_fmac_f32_e32 v59, v61, v59
	v_mul_f32_e32 v61, v60, v59
	v_fma_f32 v68, -v57, v61, v60
	v_fmac_f32_e32 v61, v68, v59
	v_fma_f32 v57, -v57, v61, v60
	v_div_fmas_f32 v57, v57, v59, v61
	v_div_fixup_f32 v57, v57, v55, 1.0
	v_mul_f32_e32 v59, v44, v57
	v_mul_f32_e32 v45, v45, v57
	v_mov_b32_e32 v44, 0
	v_cvt_pk_fp8_f32 v44, v59, v45
	v_mul_f32_e32 v46, v46, v57
	v_mul_f32_e32 v47, v47, v57
	v_mul_f32_e32 v40, v40, v57
	v_mul_f32_e32 v41, v41, v57
	v_mov_b32_e32 v45, 0
	v_cvt_pk_fp8_f32 v44, v46, v47 op_sel:[0,0,1]
	v_mul_f32_e32 v36, v36, v57
	v_mul_f32_e32 v37, v37, v57
	v_mov_b32_e32 v46, 0
	v_mul_f32_e32 v32, v32, v57
	v_mul_f32_e32 v33, v33, v57
	v_mov_b32_e32 v47, 0
	v_cvt_pk_fp8_f32 v45, v40, v41
	v_cvt_pk_fp8_f32 v46, v36, v37
	v_cvt_pk_fp8_f32 v47, v32, v33
	v_mul_f32_e32 v40, v42, v57
	v_mul_f32_e32 v41, v43, v57
	v_mul_f32_e32 v38, v38, v57
	v_mul_f32_e32 v39, v39, v57
	v_mul_f32_e32 v32, v34, v57
	v_mul_f32_e32 v33, v35, v57
	v_cvt_pk_fp8_f32 v45, v40, v41 op_sel:[0,0,1]
	v_cvt_pk_fp8_f32 v46, v38, v39 op_sel:[0,0,1]
	v_cvt_pk_fp8_f32 v47, v32, v33 op_sel:[0,0,1]
	v_ashrrev_i32_e32 v59, 31, v58
	v_lshlrev_b64 v[32:33], 10, v[58:59]
	v_lshl_add_u64 v[32:33], v[50:51], 0, v[32:33]
	global_store_dwordx4 v[32:33], v[44:47], off sc1
	s_and_b64 exec, exec, s[0:1]
	s_cbranch_execz .LBB0_185
	v_lshl_add_u64 v[32:33], v[58:59], 3, s[12:13]
	global_store_dword v[32:33], v55, off sc1
; __device__ __forceinline__ void quantise_tables(const Args& A, int gw, int NGW, int row_lo, int row_hi) {
;     ...
;         for (int q = 0; q < 4; ++q) {
;             float mx = 0.f;
; #pragma unroll
;             for (int j = 0; j < 4; ++j)
; #pragma unroll
;                 for (int e = 0; e < 4; ++e) mx = fmaxf(mx, fabsf(v[q][j][e]));
;             mx = xrow_max(mx);
;             mx = fmaxf(mx, __int_as_float(__builtin_amdgcn_mov_dpp(__float_as_int(mx), 0xB1, 0xF, 0xF, true)));
;             mx = fmaxf(mx, __int_as_float(__builtin_amdgcn_mov_dpp(__float_as_int(mx), 0x4E, 0xF, 0xF, true)));
;             mx = fmaxf(mx, __int_as_float(__builtin_amdgcn_mov_dpp(__float_as_int(mx), 0x141, 0xF, 0xF, true)));
;             mx = fmaxf(mx, __int_as_float(__builtin_amdgcn_mov_dpp(__float_as_int(mx), 0x140, 0xF, 0xF, true)));
;             const float sc = fmaxf(mx, 1e-30f) * (1.f / 256.f), inv = 1.f / sc;
;             u32x4 o4;
; #pragma unroll
;             for (int j = 0; j < 4; ++j) { int w0 = __builtin_amdgcn_cvt_pk_fp8_f32(v[q][j][0] * inv, v[q][j][1] * inv, 0, false); w0 = __builtin_amdgcn_cvt_pk_fp8_f32(v[q][j][2] * inv, v[q][j][3] * inv, w0, true); o4[j] = (unsigned)w0; }
;             if (rr[q] < row_hi) { *(u32x4*)(T8 + (size_t)rr[q] * 1024 + 16 * lane) = o4; if (lane == 0) SC[rr[q]] = sc; }
.LBB0_185:
	s_or_b64 exec, exec, s[16:17]
	s_waitcnt vmcnt(5)
	v_max3_f32 v32, |v28|, 0, |v29|
	v_max3_f32 v32, v32, |v30|, |v31|
	v_max3_f32 v32, v32, |v24|, |v25|
	v_max3_f32 v32, v32, |v26|, |v27|
	v_max3_f32 v32, v32, |v20|, |v21|
	v_max3_f32 v32, v32, |v22|, |v23|
	v_max3_f32 v32, v32, |v16|, |v17|
	v_max3_f32 v32, v32, |v18|, |v19|
	v_mov_b32_e32 v33, v32
	s_nop 1
	v_permlane16_swap_b32_e32 v32, v33
	v_max_f32_e32 v33, v33, v33
	v_max_f32_e32 v32, v32, v32
	v_max_f32_e32 v32, v32, v33
	v_mov_b32_e32 v33, v32
	s_nop 1
	v_permlane32_swap_b32_e32 v32, v33
	v_max_f32_e32 v33, v33, v33
	v_max_f32_e32 v32, v32, v32
	v_max_f32_e32 v32, v32, v33
	s_nop 1
	v_mov_b32_dpp v33, v32 quad_perm:[1,0,3,2] row_mask:0xf bank_mask:0xf bound_ctrl:1
	v_max_f32_e32 v33, v33, v33
	v_max_f32_e32 v32, v32, v33
	s_nop 1
	v_mov_b32_dpp v33, v32 quad_perm:[2,3,0,1] row_mask:0xf bank_mask:0xf bound_ctrl:1
	v_max_f32_e32 v33, v33, v33
	v_max_f32_e32 v32, v32, v33
	s_nop 1
	v_mov_b32_dpp v33, v32 row_half_mirror row_mask:0xf bank_mask:0xf bound_ctrl:1
	v_max_f32_e32 v33, v33, v33
	v_max_f32_e32 v32, v32, v33
	s_nop 1
	v_mov_b32_dpp v33, v32 row_mirror row_mask:0xf bank_mask:0xf bound_ctrl:1
	s_and_saveexec_b64 s[8:9], s[6:7]
	s_cbranch_execz .LBB0_188
	v_max3_f32 v32, v32, v33, s25
	v_mul_f32_e32 v32, 0x3b800000, v32
	v_div_scale_f32 v33, s[6:7], v32, v32, 1.0
	v_rcp_f32_e32 v34, v33
	v_div_scale_f32 v35, vcc, 1.0, v32, 1.0
	v_ashrrev_i32_e32 v57, 31, v56
	v_fma_f32 v36, -v33, v34, 1.0
	v_fmac_f32_e32 v34, v36, v34
	v_mul_f32_e32 v36, v35, v34
	v_fma_f32 v37, -v33, v36, v35
	v_fmac_f32_e32 v36, v37, v34
	v_fma_f32 v33, -v33, v36, v35
	v_div_fmas_f32 v33, v33, v34, v36
	v_div_fixup_f32 v33, v33, v32, 1.0
	v_mul_f32_e32 v34, v28, v33
	v_mul_f32_e32 v29, v29, v33
	v_mov_b32_e32 v28, 0
	v_cvt_pk_fp8_f32 v28, v34, v29
	v_mul_f32_e32 v30, v30, v33
	v_mul_f32_e32 v31, v31, v33
	v_mul_f32_e32 v24, v24, v33
	v_mul_f32_e32 v25, v25, v33
	v_mov_b32_e32 v29, 0
	v_cvt_pk_fp8_f32 v28, v30, v31 op_sel:[0,0,1]
	v_mul_f32_e32 v20, v20, v33
	v_mul_f32_e32 v21, v21, v33
	v_mov_b32_e32 v30, 0
	v_mul_f32_e32 v16, v16, v33
	v_mul_f32_e32 v17, v17, v33
	v_mov_b32_e32 v31, 0
	v_cvt_pk_fp8_f32 v29, v24, v25
	v_cvt_pk_fp8_f32 v30, v20, v21
	v_cvt_pk_fp8_f32 v31, v16, v17
	v_mul_f32_e32 v24, v26, v33
	v_mul_f32_e32 v25, v27, v33
	v_mul_f32_e32 v22, v22, v33
	v_mul_f32_e32 v23, v23, v33
	v_mul_f32_e32 v16, v18, v33
	v_mul_f32_e32 v17, v19, v33
	v_cvt_pk_fp8_f32 v29, v24, v25 op_sel:[0,0,1]
	v_cvt_pk_fp8_f32 v30, v22, v23 op_sel:[0,0,1]
	v_cvt_pk_fp8_f32 v31, v16, v17 op_sel:[0,0,1]
	v_lshlrev_b64 v[16:17], 10, v[56:57]
	v_lshl_add_u64 v[16:17], v[50:51], 0, v[16:17]
	global_store_dwordx4 v[16:17], v[28:31], off sc1
	s_and_b64 exec, exec, s[0:1]
	s_cbranch_execz .LBB0_188
	v_lshl_add_u64 v[16:17], v[56:57], 3, s[12:13]
	global_store_dword v[16:17], v32, off sc1
.LBB0_188:
	s_or_b64 exec, exec, s[8:9]
	s_waitcnt vmcnt(1)
	v_max3_f32 v16, |v12|, 0, |v13|
	v_max3_f32 v16, v16, |v14|, |v15|
	v_max3_f32 v16, v16, |v8|, |v9|
	v_max3_f32 v16, v16, |v10|, |v11|
	v_max3_f32 v16, v16, |v4|, |v5|
	v_max3_f32 v16, v16, |v6|, |v7|
	v_max3_f32 v16, v16, |v0|, |v1|
	v_max3_f32 v16, v16, |v2|, |v3|
	v_mov_b32_e32 v17, v16
	s_nop 1
	v_permlane16_swap_b32_e32 v16, v17
	v_max_f32_e32 v17, v17, v17
	v_max_f32_e32 v16, v16, v16
	v_max_f32_e32 v16, v16, v17
	v_mov_b32_e32 v17, v16
	s_nop 1
	v_permlane32_swap_b32_e32 v16, v17
	v_max_f32_e32 v17, v17, v17
	v_max_f32_e32 v16, v16, v16
	v_max_f32_e32 v16, v16, v17
	s_nop 1
	v_mov_b32_dpp v17, v16 quad_perm:[1,0,3,2] row_mask:0xf bank_mask:0xf bound_ctrl:1
	v_max_f32_e32 v17, v17, v17
	v_max_f32_e32 v16, v16, v17
	s_nop 1
	v_mov_b32_dpp v17, v16 quad_perm:[2,3,0,1] row_mask:0xf bank_mask:0xf bound_ctrl:1
	v_max_f32_e32 v17, v17, v17
	v_max_f32_e32 v16, v16, v17
	s_nop 1
	v_mov_b32_dpp v17, v16 row_half_mirror row_mask:0xf bank_mask:0xf bound_ctrl:1
	v_max_f32_e32 v17, v17, v17
	v_max_f32_e32 v16, v16, v17
	s_nop 1
	v_mov_b32_dpp v17, v16 row_mirror row_mask:0xf bank_mask:0xf bound_ctrl:1
	s_and_saveexec_b64 s[6:7], s[4:5]
	s_cbranch_execz .LBB0_179
	v_max3_f32 v16, v16, v17, s25
	v_mul_f32_e32 v16, 0x3b800000, v16
	v_div_scale_f32 v17, s[4:5], v16, v16, 1.0
	v_rcp_f32_e32 v18, v17
	v_div_scale_f32 v19, vcc, 1.0, v16, 1.0
	v_ashrrev_i32_e32 v55, 31, v54
	v_fma_f32 v20, -v17, v18, 1.0
	v_fmac_f32_e32 v18, v20, v18
	v_mul_f32_e32 v20, v19, v18
	v_fma_f32 v21, -v17, v20, v19
	v_fmac_f32_e32 v20, v21, v18
	v_fma_f32 v17, -v17, v20, v19
	v_div_fmas_f32 v17, v17, v18, v20
	v_div_fixup_f32 v17, v17, v16, 1.0
	v_mul_f32_e32 v18, v12, v17
	v_mul_f32_e32 v13, v13, v17
	v_mov_b32_e32 v12, 0
	v_cvt_pk_fp8_f32 v12, v18, v13
	v_mul_f32_e32 v14, v14, v17
	v_mul_f32_e32 v15, v15, v17
	v_mul_f32_e32 v8, v8, v17
	v_mul_f32_e32 v9, v9, v17
	v_mov_b32_e32 v13, 0
	v_cvt_pk_fp8_f32 v12, v14, v15 op_sel:[0,0,1]
	v_mul_f32_e32 v4, v4, v17
	v_mul_f32_e32 v5, v5, v17
	v_mov_b32_e32 v14, 0
	v_mul_f32_e32 v0, v0, v17
	v_mul_f32_e32 v1, v1, v17
	v_mov_b32_e32 v15, 0
	v_cvt_pk_fp8_f32 v13, v8, v9
	v_cvt_pk_fp8_f32 v14, v4, v5
	v_cvt_pk_fp8_f32 v15, v0, v1
	v_mul_f32_e32 v8, v10, v17
	v_mul_f32_e32 v9, v11, v17
	v_mul_f32_e32 v6, v6, v17
	v_mul_f32_e32 v7, v7, v17
	v_mul_f32_e32 v0, v2, v17
	v_mul_f32_e32 v1, v3, v17
	v_cvt_pk_fp8_f32 v13, v8, v9 op_sel:[0,0,1]
	v_cvt_pk_fp8_f32 v14, v6, v7 op_sel:[0,0,1]
	v_cvt_pk_fp8_f32 v15, v0, v1 op_sel:[0,0,1]
	v_lshlrev_b64 v[0:1], 10, v[54:55]
	v_lshl_add_u64 v[0:1], v[50:51], 0, v[0:1]
	global_store_dwordx4 v[0:1], v[12:15], off sc1
	s_and_b64 exec, exec, s[0:1]
	s_cbranch_execz .LBB0_179
	v_lshl_add_u64 v[0:1], v[54:55], 3, s[12:13]
	global_store_dword v[0:1], v16, off sc1
	s_branch .LBB0_179

; __device__ __forceinline__ unsigned cvt_pk_bf16(float lo, float hi) { unsigned r; asm volatile("v_cvt_pk_bf16_f32 %0, %1, %2" : "=v"(r) : "v"(lo), "v"(hi)); return r; }
;     __device__ __forceinline__ void operator()(const f32x4 (&acc)[2][2][4][2], const Unit& u, int wr, int wc, int fr, int fq) const {
;         const int row0 = u.pm * BM + wr * 64 + fr, col0 = u.pn * BM + wc * 32 + 8 * fq;
;         const float* mp = mod + (size_t)((u.pm * BM) >> 11) * 6144;
;         f32x4 g1v[2][2], csv[2][2];
; #pragma unroll
;         for (int bj = 0; bj < 2; ++bj)
; #pragma unroll
;             for (int n = 0; n < 2; ++n) { const int c = col0 + bj * HALF + 4 * n; g1v[bj][n] = *(const f32x4*)(mp + 2048 + c); csv[bj][n] = *(const f32x4*)(ng + c) * (*(const f32x4*)(mp + 4096 + c) + 1.0f); }
; #pragma unroll
;         for (int ai = 0; ai < 2; ++ai)
; #pragma unroll
;             for (int m = 0; m < 4; ++m) { const int r = row0 + ai * HALF + m * 16; float ss = 0.f;
; #pragma unroll
;                 for (int bj = 0; bj < 2; ++bj) { const int c = col0 + bj * HALF;
;                     const f32x4 xa = *(const f32x4*)(x + (size_t)r * 1024 + c), xb = *(const f32x4*)(x + (size_t)r * 1024 + c + 4);
;                     const f32x4 v0 = xa + g1v[bj][0] * acc[ai][bj][m][0], v1 = xb + g1v[bj][1] * acc[ai][bj][m][1];
;                     *(f32x4*)(out + (size_t)r * 1024 + c) = v0; *(f32x4*)(out + (size_t)r * 1024 + c + 4) = v1;
;                     ss += (v0[0] * v0[0] + v0[1] * v0[1]) + (v0[2] * v0[2] + v0[3] * v0[3]) + (v1[0] * v1[0] + v1[1] * v1[1]) + (v1[2] * v1[2] + v1[3] * v1[3]);
;                     const f32x4 a0 = v0 * csv[bj][0], a1 = v1 * csv[bj][1];
;                     u32x4 w; w.x = cvt_pk_bf16(a0[0], a0[1]); w.y = cvt_pk_bf16(a0[2], a0[3]); w.z = cvt_pk_bf16(a1[0], a1[1]); w.w = cvt_pk_bf16(a1[2], a1[3]);
;                     *(u32x4*)(a3 + (size_t)r * 1024 + c) = w; }
;                 ss += __shfl_xor(ss, 16); ss += __shfl_xor(ss, 32);
;                 if (fq == 0) rs[(size_t)r * 16 + (u.pn & 3) * 4 + wc] = ss; }
.LBB0_548:
	s_ashr_i32 s27, s38, 3
	s_mul_hi_i32 s29, s27, 0x6000
	s_mulk_i32 s27, 0x6000
	s_add_u32 s27, s86, s27
	s_addc_u32 s29, s87, s29
	v_lshl_add_u32 v164, s38, 8, v175
	v_lshl_or_b32 v160, s0, 8, v177
	s_add_u32 s40, s27, 0x2000
	v_ashrrev_i32_e32 v165, 31, v164
	s_addc_u32 s41, s29, 0
	v_ashrrev_i32_e32 v161, 31, v160
	v_lshlrev_b64 v[88:89], 12, v[164:165]
	v_lshlrev_b64 v[162:163], 2, v[160:161]
	v_lshl_add_u64 v[74:75], s[52:53], 0, v[88:89]
	s_add_u32 s38, s27, 0x4000
	v_lshl_add_u64 v[72:73], s[40:41], 0, v[162:163]
	v_lshl_add_u64 v[216:217], v[74:75], 0, v[162:163]
	s_addc_u32 s39, s29, 0
	global_load_dwordx4 v[166:169], v[216:217], off
	global_load_dwordx4 v[76:79], v[72:73], off
	s_nop 0
	global_load_dwordx4 v[72:75], v[72:73], off offset:16
	s_nop 0
	global_load_dwordx4 v[170:173], v[216:217], off offset:16
	v_lshl_add_u64 v[90:91], s[38:39], 0, v[162:163]
	global_load_dwordx4 v[182:185], v[90:91], off
	global_load_dwordx4 v[186:189], v[90:91], off offset:16
	v_lshl_add_u64 v[90:91], s[36:37], 0, v[162:163]
	global_load_dwordx4 v[190:193], v[90:91], off
	global_load_dwordx4 v[194:197], v[90:91], off offset:16
	v_or_b32_e32 v92, 0x80, v160
	v_or_b32_e32 v94, 0x84, v160
	v_ashrrev_i32_e32 v93, 31, v92
	v_lshlrev_b64 v[198:199], 11, v[164:165]
	v_ashrrev_i32_e32 v95, 31, v94
	v_lshlrev_b64 v[92:93], 2, v[92:93]
	v_lshl_add_u64 v[88:89], s[48:49], 0, v[88:89]
	v_lshl_add_u64 v[206:207], s[10:11], 0, v[198:199]
	global_load_dwordx4 v[198:201], v[90:91], off offset:528
	global_load_dwordx4 v[202:205], v[90:91], off offset:512
	v_lshl_add_u64 v[218:219], v[88:89], 0, v[162:163]
	v_lshl_add_u64 v[220:221], v[160:161], 1, v[206:207]
	v_lshl_add_u64 v[88:89], s[40:41], 0, v[92:93]
	v_lshl_add_u64 v[90:91], v[94:95], 2, s[40:41]
	v_lshl_add_u64 v[210:211], s[38:39], 0, v[92:93]
	global_load_dwordx4 v[92:95], v[88:89], off
	global_load_dwordx4 v[206:209], v[210:211], off
	s_nop 0
	global_load_dwordx4 v[210:213], v[210:211], off offset:16
	s_nop 0
	global_load_dwordx4 v[88:91], v[90:91], off
	s_lshl_b32 s0, s0, 2
	s_and_b32 s27, s0, 12
	v_lshl_add_u32 v252, v164, 12, v162
	v_add_u32_e32 v253, 0x0, v252
	global_load_dwordx4 v[228:231], v253, s[52:53] offset:512
	global_load_dwordx4 v[232:235], v253, s[52:53] offset:528
	v_add_u32_e32 v253, 0x10000, v252
	global_load_dwordx4 v[236:239], v253, s[52:53]
	global_load_dwordx4 v[240:243], v253, s[52:53] offset:16
	global_load_dwordx4 v[244:247], v253, s[52:53] offset:512
	global_load_dwordx4 v[248:251], v253, s[52:53] offset:528
	s_waitcnt vmcnt(6)
	v_pk_fma_f32 v[166:167], v[140:141], v[76:77], v[166:167]
	v_pk_fma_f32 v[168:169], v[142:143], v[78:79], v[168:169]
	v_pk_fma_f32 v[170:171], v[136:137], v[72:73], v[170:171]
	v_pk_add_f32 v[136:137], v[184:185], 1.0 op_sel_hi:[1,0]
	v_pk_add_f32 v[140:141], v[182:183], 1.0 op_sel_hi:[1,0]
	v_pk_fma_f32 v[172:173], v[138:139], v[74:75], v[172:173]
	v_pk_add_f32 v[182:183], v[188:189], 1.0 op_sel_hi:[1,0]
	v_pk_add_f32 v[184:185], v[186:187], 1.0 op_sel_hi:[1,0]
	v_pk_mul_f32 v[138:139], v[192:193], v[136:137]
	v_pk_mul_f32 v[142:143], v[190:191], v[140:141]
	v_pk_mul_f32 v[136:137], v[196:197], v[182:183]
	v_pk_mul_f32 v[140:141], v[194:195], v[184:185]
	v_pk_mul_f32 v[184:185], v[138:139], v[168:169]
	v_pk_mul_f32 v[182:183], v[142:143], v[166:167]
	global_store_dwordx4 v[218:219], v[166:169], off sc1
	global_store_dwordx4 v[218:219], v[170:173], off offset:16 sc1
	v_pk_mul_f32 v[186:187], v[136:137], v[172:173]
	v_pk_mul_f32 v[188:189], v[140:141], v[170:171]
	v_cvt_pk_bf16_f32 v182, v182, v183
	v_cvt_pk_bf16_f32 v183, v184, v185
	v_xor_b32_e32 v192, 32, v181
	v_cvt_pk_bf16_f32 v184, v188, v189
	v_cvt_pk_bf16_f32 v185, v186, v187
	global_store_dwordx4 v[220:221], v[182:185], off sc1
	s_nop 0
	s_nop 0
	v_and_b32_e32 v183, 64, v181
	v_xor_b32_e32 v182, 16, v181
	v_add_u32_e32 v183, 64, v183
	v_cmp_lt_i32_e32 vcc, v182, v183
	v_mul_f32_e32 v215, v167, v167
	v_mul_f32_e32 v216, v169, v169
	v_cndmask_b32_e32 v182, v181, v182, vcc
	v_cmp_lt_i32_e32 vcc, v192, v183
	v_mul_f32_e32 v222, v173, v173
	v_mul_f32_e32 v217, v171, v171
	v_cndmask_b32_e32 v183, v181, v192, vcc
	v_pk_add_f32 v[192:193], v[208:209], 1.0 op_sel_hi:[1,0]
	v_fmac_f32_e32 v215, v166, v166
	v_fmac_f32_e32 v216, v168, v168
	v_fmac_f32_e32 v222, v172, v172
	v_pk_mul_f32 v[172:173], v[204:205], v[192:193]
	v_fmac_f32_e32 v217, v170, v170
	v_add_f32_e32 v192, v215, v216
	v_add_f32_e32 v192, v192, v217
	v_add_f32_e32 v192, v222, v192
	v_lshlrev_b32_e32 v182, 2, v182
	v_pk_add_f32 v[194:195], v[206:207], 1.0 op_sel_hi:[1,0]
	v_pk_add_f32 v[196:197], v[212:213], 1.0 op_sel_hi:[1,0]
	v_pk_add_f32 v[206:207], v[210:211], 1.0 op_sel_hi:[1,0]
	v_pk_mul_f32 v[166:167], v[200:201], v[196:197]
	v_pk_mul_f32 v[168:169], v[198:199], v[206:207]
	v_pk_mul_f32 v[170:171], v[202:203], v[194:195]
	s_waitcnt vmcnt(5)
	v_pk_fma_f32 v[134:135], v[134:135], v[94:95], v[230:231]
	v_pk_fma_f32 v[132:133], v[132:133], v[92:93], v[228:229]
	s_waitcnt vmcnt(4)
	v_pk_fma_f32 v[128:129], v[128:129], v[88:89], v[232:233]
	v_mul_f32_e32 v186, v133, v133
	v_mul_f32_e32 v187, v135, v135
	v_pk_fma_f32 v[130:131], v[130:131], v[90:91], v[234:235]
	v_add_u32_e32 v253, 0x20000, v252
	global_load_dwordx4 v[228:231], v253, s[52:53]
	global_load_dwordx4 v[232:235], v253, s[52:53] offset:16
	v_mul_f32_e32 v188, v129, v129
	v_fmac_f32_e32 v186, v132, v132
	v_fmac_f32_e32 v187, v134, v134
	global_store_dwordx4 v[218:219], v[132:135], off offset:512 sc1
	global_store_dwordx4 v[218:219], v[128:131], off offset:528 sc1
	v_mul_f32_e32 v189, v131, v131
	v_pk_mul_f32 v[184:185], v[172:173], v[134:135]
	v_fmac_f32_e32 v188, v128, v128
	v_add_f32_e32 v134, v186, v187
	v_fmac_f32_e32 v189, v130, v130
	v_add_f32_e32 v134, v134, v188
	v_add_f32_e32 v134, v189, v134
	v_add_f32_e32 v188, v192, v134
	ds_bpermute_b32 v189, v182, v188
	v_pk_mul_f32 v[186:187], v[166:167], v[130:131]
	v_pk_mul_f32 v[134:135], v[168:169], v[128:129]
	v_lshlrev_b32_e32 v130, 2, v183
	v_pk_mul_f32 v[132:133], v[170:171], v[132:133]
	s_waitcnt lgkmcnt(0)
	v_add_f32_e32 v128, v188, v189
	ds_bpermute_b32 v129, v130, v128
	v_cvt_pk_bf16_f32 v132, v132, v133
	v_cvt_pk_bf16_f32 v133, v184, v185
	v_cvt_pk_bf16_f32 v134, v134, v135
	v_cvt_pk_bf16_f32 v135, v186, v187
	global_store_dwordx4 v[220:221], v[132:135], off offset:256 sc1
	s_and_saveexec_b64 s[38:39], s[6:7]
	s_cbranch_execz .LBB0_550
	v_lshlrev_b64 v[132:133], 6, v[164:165]
	v_lshl_add_u64 v[132:133], s[12:13], 0, v[132:133]
	s_lshl_b32 s0, s27, 2
	v_lshl_add_u64 v[132:133], v[132:133], 0, s[0:1]
	s_lshl_b32 s0, s64, 2
	v_lshl_add_u64 v[132:133], v[132:133], 0, s[0:1]
	s_waitcnt lgkmcnt(0)
	v_add_f32_e32 v128, v128, v129
	global_store_dword v[132:133], v128, off sc1
; __device__ __forceinline__ unsigned cvt_pk_bf16(float lo, float hi) { unsigned r; asm volatile("v_cvt_pk_bf16_f32 %0, %1, %2" : "=v"(r) : "v"(lo), "v"(hi)); return r; }
;     __device__ __forceinline__ void operator()(const f32x4 (&acc)[2][2][4][2], const Unit& u, int wr, int wc, int fr, int fq) const {
;     ...
;             for (int m = 0; m < 4; ++m) { const int r = row0 + ai * HALF + m * 16; float ss = 0.f;
; #pragma unroll
;                 for (int bj = 0; bj < 2; ++bj) { const int c = col0 + bj * HALF;
;                     const f32x4 xa = *(const f32x4*)(x + (size_t)r * 1024 + c), xb = *(const f32x4*)(x + (size_t)r * 1024 + c + 4);
;                     const f32x4 v0 = xa + g1v[bj][0] * acc[ai][bj][m][0], v1 = xb + g1v[bj][1] * acc[ai][bj][m][1];
;                     *(f32x4*)(out + (size_t)r * 1024 + c) = v0; *(f32x4*)(out + (size_t)r * 1024 + c + 4) = v1;
;                     ss += (v0[0] * v0[0] + v0[1] * v0[1]) + (v0[2] * v0[2] + v0[3] * v0[3]) + (v1[0] * v1[0] + v1[1] * v1[1]) + (v1[2] * v1[2] + v1[3] * v1[3]);
;                     const f32x4 a0 = v0 * csv[bj][0], a1 = v1 * csv[bj][1];
;                     u32x4 w; w.x = cvt_pk_bf16(a0[0], a0[1]); w.y = cvt_pk_bf16(a0[2], a0[3]); w.z = cvt_pk_bf16(a1[0], a1[1]); w.w = cvt_pk_bf16(a1[2], a1[3]);
;                     *(u32x4*)(a3 + (size_t)r * 1024 + c) = w; }
;                 ss += __shfl_xor(ss, 16); ss += __shfl_xor(ss, 32);
;                 if (fq == 0) rs[(size_t)r * 16 + (u.pn & 3) * 4 + wc] = ss; }
.LBB0_550:
	s_or_b64 exec, exec, s[38:39]
	v_or_b32_e32 v128, 16, v164
	s_waitcnt lgkmcnt(0)
	v_ashrrev_i32_e32 v129, 31, v128
	v_lshlrev_b64 v[188:189], 12, v[128:129]
	v_lshl_add_u64 v[132:133], s[52:53], 0, v[188:189]
	v_lshl_add_u64 v[190:191], v[132:133], 0, v[162:163]
	s_nop 0
	s_nop 0
	v_lshlrev_b64 v[192:193], 11, v[128:129]
	v_lshl_add_u64 v[188:189], s[48:49], 0, v[188:189]
	v_lshl_add_u64 v[192:193], s[10:11], 0, v[192:193]
	v_lshl_add_u64 v[188:189], v[188:189], 0, v[162:163]
	v_lshl_add_u64 v[192:193], v[160:161], 1, v[192:193]
	s_waitcnt vmcnt(5)
	v_pk_fma_f32 v[126:127], v[126:127], v[78:79], v[238:239]
	v_pk_fma_f32 v[124:125], v[124:125], v[76:77], v[236:237]
	s_waitcnt vmcnt(4)
	v_pk_fma_f32 v[122:123], v[122:123], v[74:75], v[242:243]
	v_pk_fma_f32 v[120:121], v[120:121], v[72:73], v[240:241]
	v_add_u32_e32 v253, 0x20000, v252
	global_load_dwordx4 v[236:239], v253, s[52:53] offset:512
	global_load_dwordx4 v[240:243], v253, s[52:53] offset:528
	v_pk_mul_f32 v[134:135], v[138:139], v[126:127]
	v_pk_mul_f32 v[132:133], v[142:143], v[124:125]
	global_store_dwordx4 v[188:189], v[124:127], off sc1
	global_store_dwordx4 v[188:189], v[120:123], off offset:16 sc1
	v_pk_mul_f32 v[184:185], v[136:137], v[122:123]
	v_pk_mul_f32 v[186:187], v[140:141], v[120:121]
	v_cvt_pk_bf16_f32 v132, v132, v133
	v_cvt_pk_bf16_f32 v133, v134, v135
	v_mul_f32_e32 v125, v125, v125
	v_cvt_pk_bf16_f32 v134, v186, v187
	v_cvt_pk_bf16_f32 v135, v184, v185
	global_store_dwordx4 v[192:193], v[132:135], off sc1
	s_nop 0
	s_nop 0
	v_mul_f32_e32 v127, v127, v127
	v_mul_f32_e32 v121, v121, v121
	v_fmac_f32_e32 v125, v124, v124
	v_fmac_f32_e32 v127, v126, v126
	v_mul_f32_e32 v123, v123, v123
	v_fmac_f32_e32 v121, v120, v120
	v_add_f32_e32 v120, v125, v127
	v_fmac_f32_e32 v123, v122, v122
	v_add_f32_e32 v120, v120, v121
	v_add_f32_e32 v120, v123, v120
	s_waitcnt vmcnt(5)
	v_pk_fma_f32 v[118:119], v[118:119], v[94:95], v[246:247]
	v_pk_fma_f32 v[116:117], v[116:117], v[92:93], v[244:245]
	s_waitcnt vmcnt(4)
	v_pk_fma_f32 v[112:113], v[112:113], v[88:89], v[248:249]
	v_mul_f32_e32 v121, v117, v117
	v_mul_f32_e32 v122, v119, v119
	v_pk_fma_f32 v[114:115], v[114:115], v[90:91], v[250:251]
	v_add_u32_e32 v253, 0x30000, v252
	global_load_dwordx4 v[244:247], v253, s[52:53]
	global_load_dwordx4 v[248:251], v253, s[52:53] offset:16
	v_mul_f32_e32 v123, v113, v113
	v_fmac_f32_e32 v121, v116, v116
	v_fmac_f32_e32 v122, v118, v118
	v_mul_f32_e32 v124, v115, v115
	v_fmac_f32_e32 v123, v112, v112
	v_add_f32_e32 v121, v121, v122
	v_fmac_f32_e32 v124, v114, v114
	v_add_f32_e32 v121, v121, v123
	v_add_f32_e32 v121, v124, v121
	v_add_f32_e32 v124, v120, v121
	ds_bpermute_b32 v125, v182, v124
	global_store_dwordx4 v[188:189], v[116:119], off offset:512 sc1
	global_store_dwordx4 v[188:189], v[112:115], off offset:528 sc1
	v_pk_mul_f32 v[122:123], v[168:169], v[112:113]
	v_pk_mul_f32 v[116:117], v[170:171], v[116:117]
	v_pk_mul_f32 v[118:119], v[172:173], v[118:119]
	s_waitcnt lgkmcnt(0)
	v_add_f32_e32 v112, v124, v125
	ds_bpermute_b32 v113, v130, v112
	v_pk_mul_f32 v[120:121], v[166:167], v[114:115]
	v_cvt_pk_bf16_f32 v114, v116, v117
	v_cvt_pk_bf16_f32 v115, v118, v119
	v_cvt_pk_bf16_f32 v116, v122, v123
	s_nop 0
	v_cvt_pk_bf16_f32 v117, v120, v121
	global_store_dwordx4 v[192:193], v[114:117], off offset:256 sc1
	s_and_saveexec_b64 s[38:39], s[6:7]
	s_cbranch_execz .LBB0_552
	v_lshlrev_b64 v[114:115], 6, v[128:129]
	v_lshl_add_u64 v[114:115], s[12:13], 0, v[114:115]
	s_lshl_b32 s0, s27, 2
	v_lshl_add_u64 v[114:115], v[114:115], 0, s[0:1]
	s_lshl_b32 s0, s64, 2
	v_lshl_add_u64 v[114:115], v[114:115], 0, s[0:1]
	s_waitcnt lgkmcnt(0)
	v_add_f32_e32 v112, v112, v113
	global_store_dword v[114:115], v112, off sc1
.LBB0_552:
	s_or_b64 exec, exec, s[38:39]
	v_or_b32_e32 v112, 32, v164
	s_waitcnt lgkmcnt(0)
	v_ashrrev_i32_e32 v113, 31, v112
	v_lshlrev_b64 v[122:123], 12, v[112:113]
	v_lshl_add_u64 v[114:115], s[52:53], 0, v[122:123]
	v_lshl_add_u64 v[124:125], v[114:115], 0, v[162:163]
	s_nop 0
	s_nop 0
	v_lshlrev_b64 v[126:127], 11, v[112:113]
	v_lshl_add_u64 v[122:123], s[48:49], 0, v[122:123]
	v_lshl_add_u64 v[126:127], s[10:11], 0, v[126:127]
	v_lshl_add_u64 v[122:123], v[122:123], 0, v[162:163]
	v_lshl_add_u64 v[126:127], v[160:161], 1, v[126:127]
	s_waitcnt vmcnt(5)
	v_pk_fma_f32 v[110:111], v[110:111], v[78:79], v[230:231]
	v_pk_fma_f32 v[108:109], v[108:109], v[76:77], v[228:229]
	s_waitcnt vmcnt(4)
	v_pk_fma_f32 v[106:107], v[106:107], v[74:75], v[234:235]
	v_pk_fma_f32 v[104:105], v[104:105], v[72:73], v[232:233]
	v_add_u32_e32 v253, 0x30000, v252
	global_load_dwordx4 v[228:231], v253, s[52:53] offset:512
	global_load_dwordx4 v[232:235], v253, s[52:53] offset:528
	v_pk_mul_f32 v[116:117], v[138:139], v[110:111]
	v_pk_mul_f32 v[114:115], v[142:143], v[108:109]
	global_store_dwordx4 v[122:123], v[108:111], off sc1
	global_store_dwordx4 v[122:123], v[104:107], off offset:16 sc1
	v_pk_mul_f32 v[118:119], v[136:137], v[106:107]
	v_pk_mul_f32 v[120:121], v[140:141], v[104:105]
	v_cvt_pk_bf16_f32 v114, v114, v115
	v_cvt_pk_bf16_f32 v115, v116, v117
	v_mul_f32_e32 v109, v109, v109
	v_cvt_pk_bf16_f32 v116, v120, v121
	v_cvt_pk_bf16_f32 v117, v118, v119
	global_store_dwordx4 v[126:127], v[114:117], off sc1
	s_nop 0
	s_nop 0
	v_mul_f32_e32 v111, v111, v111
	v_mul_f32_e32 v105, v105, v105
	v_fmac_f32_e32 v109, v108, v108
	v_fmac_f32_e32 v111, v110, v110
	v_mul_f32_e32 v107, v107, v107
	v_fmac_f32_e32 v105, v104, v104
	v_add_f32_e32 v104, v109, v111
	v_fmac_f32_e32 v107, v106, v106
	v_add_f32_e32 v104, v104, v105
	v_add_f32_e32 v104, v107, v104
	s_waitcnt vmcnt(5)
; __device__ __forceinline__ unsigned cvt_pk_bf16(float lo, float hi) { unsigned r; asm volatile("v_cvt_pk_bf16_f32 %0, %1, %2" : "=v"(r) : "v"(lo), "v"(hi)); return r; }
;     __device__ __forceinline__ void operator()(const f32x4 (&acc)[2][2][4][2], const Unit& u, int wr, int wc, int fr, int fq) const {
;     ...
;             for (int m = 0; m < 4; ++m) { const int r = row0 + ai * HALF + m * 16; float ss = 0.f;
; #pragma unroll
;                 for (int bj = 0; bj < 2; ++bj) { const int c = col0 + bj * HALF;
;                     const f32x4 xa = *(const f32x4*)(x + (size_t)r * 1024 + c), xb = *(const f32x4*)(x + (size_t)r * 1024 + c + 4);
;                     const f32x4 v0 = xa + g1v[bj][0] * acc[ai][bj][m][0], v1 = xb + g1v[bj][1] * acc[ai][bj][m][1];
;                     *(f32x4*)(out + (size_t)r * 1024 + c) = v0; *(f32x4*)(out + (size_t)r * 1024 + c + 4) = v1;
;                     ss += (v0[0] * v0[0] + v0[1] * v0[1]) + (v0[2] * v0[2] + v0[3] * v0[3]) + (v1[0] * v1[0] + v1[1] * v1[1]) + (v1[2] * v1[2] + v1[3] * v1[3]);
;                     const f32x4 a0 = v0 * csv[bj][0], a1 = v1 * csv[bj][1];
;                     u32x4 w; w.x = cvt_pk_bf16(a0[0], a0[1]); w.y = cvt_pk_bf16(a0[2], a0[3]); w.z = cvt_pk_bf16(a1[0], a1[1]); w.w = cvt_pk_bf16(a1[2], a1[3]);
;                     *(u32x4*)(a3 + (size_t)r * 1024 + c) = w; }
;                 ss += __shfl_xor(ss, 16); ss += __shfl_xor(ss, 32);
;                 if (fq == 0) rs[(size_t)r * 16 + (u.pn & 3) * 4 + wc] = ss; }
	v_pk_fma_f32 v[102:103], v[102:103], v[94:95], v[238:239]
	v_pk_fma_f32 v[100:101], v[100:101], v[92:93], v[236:237]
	s_waitcnt vmcnt(4)
	v_pk_fma_f32 v[96:97], v[96:97], v[88:89], v[240:241]
	v_mul_f32_e32 v105, v101, v101
	v_mul_f32_e32 v106, v103, v103
	v_pk_fma_f32 v[98:99], v[98:99], v[90:91], v[242:243]
	v_add_u32_e32 v253, 0x80000, v252
	global_load_dwordx4 v[236:239], v253, s[52:53]
	global_load_dwordx4 v[240:243], v253, s[52:53] offset:16
	v_mul_f32_e32 v107, v97, v97
	v_fmac_f32_e32 v105, v100, v100
	v_fmac_f32_e32 v106, v102, v102
	v_mul_f32_e32 v108, v99, v99
	v_fmac_f32_e32 v107, v96, v96
	v_add_f32_e32 v105, v105, v106
	v_fmac_f32_e32 v108, v98, v98
	v_add_f32_e32 v105, v105, v107
	v_add_f32_e32 v105, v108, v105
	v_add_f32_e32 v108, v104, v105
	ds_bpermute_b32 v109, v182, v108
	global_store_dwordx4 v[122:123], v[100:103], off offset:512 sc1
	global_store_dwordx4 v[122:123], v[96:99], off offset:528 sc1
	v_pk_mul_f32 v[106:107], v[168:169], v[96:97]
	v_pk_mul_f32 v[100:101], v[170:171], v[100:101]
	v_pk_mul_f32 v[102:103], v[172:173], v[102:103]
	s_waitcnt lgkmcnt(0)
	v_add_f32_e32 v96, v108, v109
	ds_bpermute_b32 v97, v130, v96
	v_pk_mul_f32 v[104:105], v[166:167], v[98:99]
	v_cvt_pk_bf16_f32 v98, v100, v101
	v_cvt_pk_bf16_f32 v99, v102, v103
	v_cvt_pk_bf16_f32 v100, v106, v107
	s_nop 0
	v_cvt_pk_bf16_f32 v101, v104, v105
	global_store_dwordx4 v[126:127], v[98:101], off offset:256 sc1
	s_and_saveexec_b64 s[38:39], s[6:7]
	s_cbranch_execz .LBB0_554
	v_lshlrev_b64 v[98:99], 6, v[112:113]
	v_lshl_add_u64 v[98:99], s[12:13], 0, v[98:99]
	s_lshl_b32 s0, s27, 2
	v_lshl_add_u64 v[98:99], v[98:99], 0, s[0:1]
	s_lshl_b32 s0, s64, 2
	v_lshl_add_u64 v[98:99], v[98:99], 0, s[0:1]
	s_waitcnt lgkmcnt(0)
	v_add_f32_e32 v96, v96, v97
	global_store_dword v[98:99], v96, off sc1
.LBB0_554:
	s_or_b64 exec, exec, s[38:39]
	v_or_b32_e32 v96, 48, v164
	s_waitcnt lgkmcnt(0)
	v_ashrrev_i32_e32 v97, 31, v96
	v_lshlrev_b64 v[106:107], 12, v[96:97]
	v_lshl_add_u64 v[98:99], s[52:53], 0, v[106:107]
	v_lshl_add_u64 v[108:109], v[98:99], 0, v[162:163]
	s_nop 0
	s_nop 0
	v_lshlrev_b64 v[110:111], 11, v[96:97]
	v_lshl_add_u64 v[106:107], s[48:49], 0, v[106:107]
	v_lshl_add_u64 v[110:111], s[10:11], 0, v[110:111]
	v_lshl_add_u64 v[106:107], v[106:107], 0, v[162:163]
	v_lshl_add_u64 v[110:111], v[160:161], 1, v[110:111]
	s_waitcnt vmcnt(5)
	v_pk_fma_f32 v[86:87], v[86:87], v[78:79], v[246:247]
	v_pk_fma_f32 v[84:85], v[84:85], v[76:77], v[244:245]
	s_waitcnt vmcnt(4)
	v_pk_fma_f32 v[82:83], v[82:83], v[74:75], v[250:251]
	v_pk_fma_f32 v[80:81], v[80:81], v[72:73], v[248:249]
	v_add_u32_e32 v253, 0x80000, v252
	global_load_dwordx4 v[244:247], v253, s[52:53] offset:512
	global_load_dwordx4 v[248:251], v253, s[52:53] offset:528
	v_pk_mul_f32 v[100:101], v[138:139], v[86:87]
	v_pk_mul_f32 v[98:99], v[142:143], v[84:85]
	global_store_dwordx4 v[106:107], v[84:87], off sc1
	global_store_dwordx4 v[106:107], v[80:83], off offset:16 sc1
	v_pk_mul_f32 v[102:103], v[136:137], v[82:83]
	v_pk_mul_f32 v[104:105], v[140:141], v[80:81]
	v_cvt_pk_bf16_f32 v98, v98, v99
	v_cvt_pk_bf16_f32 v99, v100, v101
	v_mul_f32_e32 v85, v85, v85
	v_cvt_pk_bf16_f32 v100, v104, v105
	v_cvt_pk_bf16_f32 v101, v102, v103
	global_store_dwordx4 v[110:111], v[98:101], off sc1
	s_nop 0
	s_nop 0
	v_mul_f32_e32 v87, v87, v87
	v_mul_f32_e32 v81, v81, v81
	v_fmac_f32_e32 v85, v84, v84
	v_fmac_f32_e32 v87, v86, v86
	v_mul_f32_e32 v83, v83, v83
	v_fmac_f32_e32 v81, v80, v80
	v_add_f32_e32 v80, v85, v87
	v_fmac_f32_e32 v83, v82, v82
	v_add_f32_e32 v80, v80, v81
	v_add_f32_e32 v80, v83, v80
	s_waitcnt vmcnt(5)
	v_pk_fma_f32 v[70:71], v[70:71], v[94:95], v[230:231]
	v_pk_fma_f32 v[68:69], v[68:69], v[92:93], v[228:229]
	s_waitcnt vmcnt(4)
	v_pk_fma_f32 v[64:65], v[64:65], v[88:89], v[232:233]
	v_mul_f32_e32 v81, v69, v69
	v_mul_f32_e32 v82, v71, v71
	v_pk_fma_f32 v[66:67], v[66:67], v[90:91], v[234:235]
	v_add_u32_e32 v253, 0x90000, v252
	global_load_dwordx4 v[228:231], v253, s[52:53]
	global_load_dwordx4 v[232:235], v253, s[52:53] offset:16
	v_mul_f32_e32 v83, v65, v65
	v_fmac_f32_e32 v81, v68, v68
	v_fmac_f32_e32 v82, v70, v70
	v_mul_f32_e32 v84, v67, v67
	v_fmac_f32_e32 v83, v64, v64
	v_add_f32_e32 v81, v81, v82
	v_fmac_f32_e32 v84, v66, v66
	v_add_f32_e32 v81, v81, v83
	v_add_f32_e32 v81, v84, v81
	v_add_f32_e32 v84, v80, v81
	ds_bpermute_b32 v85, v182, v84
	global_store_dwordx4 v[106:107], v[68:71], off offset:512 sc1
	global_store_dwordx4 v[106:107], v[64:67], off offset:528 sc1
	v_pk_mul_f32 v[82:83], v[168:169], v[64:65]
	v_pk_mul_f32 v[68:69], v[170:171], v[68:69]
	v_pk_mul_f32 v[70:71], v[172:173], v[70:71]
	s_waitcnt lgkmcnt(0)
	v_add_f32_e32 v64, v84, v85
	ds_bpermute_b32 v65, v130, v64
	v_pk_mul_f32 v[80:81], v[166:167], v[66:67]
	v_cvt_pk_bf16_f32 v66, v68, v69
	v_cvt_pk_bf16_f32 v67, v70, v71
	v_cvt_pk_bf16_f32 v68, v82, v83
	s_nop 0
	v_cvt_pk_bf16_f32 v69, v80, v81
	global_store_dwordx4 v[110:111], v[66:69], off offset:256 sc1
	s_and_saveexec_b64 s[38:39], s[6:7]
	s_cbranch_execz .LBB0_556
	v_lshlrev_b64 v[66:67], 6, v[96:97]
	v_lshl_add_u64 v[66:67], s[12:13], 0, v[66:67]
	s_lshl_b32 s0, s27, 2
	v_lshl_add_u64 v[66:67], v[66:67], 0, s[0:1]
	s_lshl_b32 s0, s64, 2
	v_lshl_add_u64 v[66:67], v[66:67], 0, s[0:1]
	s_waitcnt lgkmcnt(0)
	v_add_f32_e32 v64, v64, v65
	global_store_dword v[66:67], v64, off sc1
; __device__ __forceinline__ unsigned cvt_pk_bf16(float lo, float hi) { unsigned r; asm volatile("v_cvt_pk_bf16_f32 %0, %1, %2" : "=v"(r) : "v"(lo), "v"(hi)); return r; }
;     __device__ __forceinline__ void operator()(const f32x4 (&acc)[2][2][4][2], const Unit& u, int wr, int wc, int fr, int fq) const {
;     ...
;             for (int m = 0; m < 4; ++m) { const int r = row0 + ai * HALF + m * 16; float ss = 0.f;
; #pragma unroll
;                 for (int bj = 0; bj < 2; ++bj) { const int c = col0 + bj * HALF;
;                     const f32x4 xa = *(const f32x4*)(x + (size_t)r * 1024 + c), xb = *(const f32x4*)(x + (size_t)r * 1024 + c + 4);
;                     const f32x4 v0 = xa + g1v[bj][0] * acc[ai][bj][m][0], v1 = xb + g1v[bj][1] * acc[ai][bj][m][1];
;                     *(f32x4*)(out + (size_t)r * 1024 + c) = v0; *(f32x4*)(out + (size_t)r * 1024 + c + 4) = v1;
;                     ss += (v0[0] * v0[0] + v0[1] * v0[1]) + (v0[2] * v0[2] + v0[3] * v0[3]) + (v1[0] * v1[0] + v1[1] * v1[1]) + (v1[2] * v1[2] + v1[3] * v1[3]);
;                     const f32x4 a0 = v0 * csv[bj][0], a1 = v1 * csv[bj][1];
;                     u32x4 w; w.x = cvt_pk_bf16(a0[0], a0[1]); w.y = cvt_pk_bf16(a0[2], a0[3]); w.z = cvt_pk_bf16(a1[0], a1[1]); w.w = cvt_pk_bf16(a1[2], a1[3]);
;                     *(u32x4*)(a3 + (size_t)r * 1024 + c) = w; }
;                 ss += __shfl_xor(ss, 16); ss += __shfl_xor(ss, 32);
;                 if (fq == 0) rs[(size_t)r * 16 + (u.pn & 3) * 4 + wc] = ss; }
.LBB0_556:
	s_or_b64 exec, exec, s[38:39]
	v_add_u32_e32 v64, 0x80, v164
	s_waitcnt lgkmcnt(0)
	v_ashrrev_i32_e32 v65, 31, v64
	v_lshlrev_b64 v[70:71], 12, v[64:65]
	v_lshl_add_u64 v[66:67], s[52:53], 0, v[70:71]
	v_lshl_add_u64 v[84:85], v[66:67], 0, v[162:163]
	s_nop 0
	s_nop 0
	v_lshlrev_b64 v[86:87], 11, v[64:65]
	v_lshl_add_u64 v[70:71], s[48:49], 0, v[70:71]
	v_lshl_add_u64 v[86:87], s[10:11], 0, v[86:87]
	v_lshl_add_u64 v[70:71], v[70:71], 0, v[162:163]
	v_lshl_add_u64 v[86:87], v[160:161], 1, v[86:87]
	s_waitcnt vmcnt(5)
	v_pk_fma_f32 v[62:63], v[62:63], v[78:79], v[238:239]
	v_pk_fma_f32 v[60:61], v[60:61], v[76:77], v[236:237]
	s_waitcnt vmcnt(4)
	v_pk_fma_f32 v[58:59], v[58:59], v[74:75], v[242:243]
	v_pk_fma_f32 v[56:57], v[56:57], v[72:73], v[240:241]
	v_add_u32_e32 v253, 0x90000, v252
	global_load_dwordx4 v[236:239], v253, s[52:53] offset:512
	global_load_dwordx4 v[240:243], v253, s[52:53] offset:528
	v_pk_mul_f32 v[68:69], v[138:139], v[62:63]
	v_pk_mul_f32 v[66:67], v[142:143], v[60:61]
	global_store_dwordx4 v[70:71], v[60:63], off sc1
	global_store_dwordx4 v[70:71], v[56:59], off offset:16 sc1
	v_pk_mul_f32 v[80:81], v[136:137], v[58:59]
	v_pk_mul_f32 v[82:83], v[140:141], v[56:57]
	v_cvt_pk_bf16_f32 v66, v66, v67
	v_cvt_pk_bf16_f32 v67, v68, v69
	v_mul_f32_e32 v61, v61, v61
	v_cvt_pk_bf16_f32 v68, v82, v83
	v_cvt_pk_bf16_f32 v69, v80, v81
	global_store_dwordx4 v[86:87], v[66:69], off sc1
	s_nop 0
	s_nop 0
	v_mul_f32_e32 v63, v63, v63
	v_mul_f32_e32 v57, v57, v57
	v_fmac_f32_e32 v61, v60, v60
	v_fmac_f32_e32 v63, v62, v62
	v_mul_f32_e32 v59, v59, v59
	v_fmac_f32_e32 v57, v56, v56
	v_add_f32_e32 v56, v61, v63
	v_fmac_f32_e32 v59, v58, v58
	v_add_f32_e32 v56, v56, v57
	v_add_f32_e32 v56, v59, v56
	s_waitcnt vmcnt(5)
	v_pk_fma_f32 v[54:55], v[54:55], v[94:95], v[246:247]
	v_pk_fma_f32 v[52:53], v[52:53], v[92:93], v[244:245]
	s_waitcnt vmcnt(4)
	v_pk_fma_f32 v[48:49], v[48:49], v[88:89], v[248:249]
	v_mul_f32_e32 v57, v53, v53
	v_mul_f32_e32 v58, v55, v55
	v_pk_fma_f32 v[50:51], v[50:51], v[90:91], v[250:251]
	v_add_u32_e32 v253, 0xa0000, v252
	global_load_dwordx4 v[244:247], v253, s[52:53]
	global_load_dwordx4 v[248:251], v253, s[52:53] offset:16
	v_mul_f32_e32 v59, v49, v49
	v_fmac_f32_e32 v57, v52, v52
	v_fmac_f32_e32 v58, v54, v54
	v_mul_f32_e32 v60, v51, v51
	v_fmac_f32_e32 v59, v48, v48
	v_add_f32_e32 v57, v57, v58
	v_fmac_f32_e32 v60, v50, v50
	v_add_f32_e32 v57, v57, v59
	v_add_f32_e32 v57, v60, v57
	v_add_f32_e32 v60, v56, v57
	ds_bpermute_b32 v61, v182, v60
	global_store_dwordx4 v[70:71], v[52:55], off offset:512 sc1
	global_store_dwordx4 v[70:71], v[48:51], off offset:528 sc1
	v_pk_mul_f32 v[58:59], v[168:169], v[48:49]
	v_pk_mul_f32 v[52:53], v[170:171], v[52:53]
	v_pk_mul_f32 v[54:55], v[172:173], v[54:55]
	s_waitcnt lgkmcnt(0)
	v_add_f32_e32 v48, v60, v61
	ds_bpermute_b32 v49, v130, v48
	v_pk_mul_f32 v[56:57], v[166:167], v[50:51]
	v_cvt_pk_bf16_f32 v50, v52, v53
	v_cvt_pk_bf16_f32 v51, v54, v55
	v_cvt_pk_bf16_f32 v52, v58, v59
	s_nop 0
	v_cvt_pk_bf16_f32 v53, v56, v57
	global_store_dwordx4 v[86:87], v[50:53], off offset:256 sc1
	s_and_saveexec_b64 s[38:39], s[6:7]
	s_cbranch_execz .LBB0_558
	v_lshlrev_b64 v[50:51], 6, v[64:65]
	v_lshl_add_u64 v[50:51], s[12:13], 0, v[50:51]
	s_lshl_b32 s0, s27, 2
	v_lshl_add_u64 v[50:51], v[50:51], 0, s[0:1]
	s_lshl_b32 s0, s64, 2
	v_lshl_add_u64 v[50:51], v[50:51], 0, s[0:1]
	s_waitcnt lgkmcnt(0)
	v_add_f32_e32 v48, v48, v49
	global_store_dword v[50:51], v48, off sc1
.LBB0_558:
	s_or_b64 exec, exec, s[38:39]
	v_add_u32_e32 v48, 0x90, v164
	s_waitcnt lgkmcnt(0)
	v_ashrrev_i32_e32 v49, 31, v48
	v_lshlrev_b64 v[58:59], 12, v[48:49]
	v_lshl_add_u64 v[50:51], s[52:53], 0, v[58:59]
	v_lshl_add_u64 v[60:61], v[50:51], 0, v[162:163]
	s_nop 0
	s_nop 0
	v_lshlrev_b64 v[62:63], 11, v[48:49]
	v_lshl_add_u64 v[58:59], s[48:49], 0, v[58:59]
	v_lshl_add_u64 v[62:63], s[10:11], 0, v[62:63]
	v_lshl_add_u64 v[58:59], v[58:59], 0, v[162:163]
	v_lshl_add_u64 v[62:63], v[160:161], 1, v[62:63]
	s_waitcnt vmcnt(5)
	v_pk_fma_f32 v[46:47], v[46:47], v[78:79], v[230:231]
	v_pk_fma_f32 v[44:45], v[44:45], v[76:77], v[228:229]
	s_waitcnt vmcnt(4)
	v_pk_fma_f32 v[42:43], v[42:43], v[74:75], v[234:235]
	v_pk_fma_f32 v[40:41], v[40:41], v[72:73], v[232:233]
	v_add_u32_e32 v253, 0xa0000, v252
	global_load_dwordx4 v[228:231], v253, s[52:53] offset:512
	global_load_dwordx4 v[232:235], v253, s[52:53] offset:528
	v_pk_mul_f32 v[52:53], v[138:139], v[46:47]
	v_pk_mul_f32 v[50:51], v[142:143], v[44:45]
	global_store_dwordx4 v[58:59], v[44:47], off sc1
	global_store_dwordx4 v[58:59], v[40:43], off offset:16 sc1
	v_pk_mul_f32 v[54:55], v[136:137], v[42:43]
	v_pk_mul_f32 v[56:57], v[140:141], v[40:41]
	v_cvt_pk_bf16_f32 v50, v50, v51
	v_cvt_pk_bf16_f32 v51, v52, v53
	v_mul_f32_e32 v45, v45, v45
	v_cvt_pk_bf16_f32 v52, v56, v57
	v_cvt_pk_bf16_f32 v53, v54, v55
	global_store_dwordx4 v[62:63], v[50:53], off sc1
	s_nop 0
	s_nop 0
	v_mul_f32_e32 v47, v47, v47
	v_mul_f32_e32 v41, v41, v41
	v_fmac_f32_e32 v45, v44, v44
	v_fmac_f32_e32 v47, v46, v46
	v_mul_f32_e32 v43, v43, v43
	v_fmac_f32_e32 v41, v40, v40
	v_add_f32_e32 v40, v45, v47
	v_fmac_f32_e32 v43, v42, v42
	v_add_f32_e32 v40, v40, v41
	v_add_f32_e32 v40, v43, v40
	s_waitcnt vmcnt(5)
	v_pk_fma_f32 v[38:39], v[38:39], v[94:95], v[238:239]
	v_pk_fma_f32 v[36:37], v[36:37], v[92:93], v[236:237]
	s_waitcnt vmcnt(4)
	v_pk_fma_f32 v[32:33], v[32:33], v[88:89], v[240:241]
	v_mul_f32_e32 v41, v37, v37
	v_mul_f32_e32 v42, v39, v39
	v_pk_fma_f32 v[34:35], v[34:35], v[90:91], v[242:243]
	v_add_u32_e32 v253, 0xb0000, v252
	global_load_dwordx4 v[236:239], v253, s[52:53]
	global_load_dwordx4 v[240:243], v253, s[52:53] offset:16
	v_mul_f32_e32 v43, v33, v33
	v_fmac_f32_e32 v41, v36, v36
	v_fmac_f32_e32 v42, v38, v38
	v_mul_f32_e32 v44, v35, v35
	v_fmac_f32_e32 v43, v32, v32
	v_add_f32_e32 v41, v41, v42
	v_fmac_f32_e32 v44, v34, v34
	v_add_f32_e32 v41, v41, v43
	v_add_f32_e32 v41, v44, v41
	v_add_f32_e32 v44, v40, v41
	ds_bpermute_b32 v45, v182, v44
	global_store_dwordx4 v[58:59], v[36:39], off offset:512 sc1
	global_store_dwordx4 v[58:59], v[32:35], off offset:528 sc1
	v_pk_mul_f32 v[42:43], v[168:169], v[32:33]
	v_pk_mul_f32 v[36:37], v[170:171], v[36:37]
	v_pk_mul_f32 v[38:39], v[172:173], v[38:39]
	s_waitcnt lgkmcnt(0)
	v_add_f32_e32 v32, v44, v45
	ds_bpermute_b32 v33, v130, v32
	v_pk_mul_f32 v[40:41], v[166:167], v[34:35]
	v_cvt_pk_bf16_f32 v34, v36, v37
	v_cvt_pk_bf16_f32 v35, v38, v39
	v_cvt_pk_bf16_f32 v36, v42, v43
	s_nop 0
	v_cvt_pk_bf16_f32 v37, v40, v41
	global_store_dwordx4 v[62:63], v[34:37], off offset:256 sc1
	s_and_saveexec_b64 s[38:39], s[6:7]
	s_cbranch_execz .LBB0_560
	v_lshlrev_b64 v[34:35], 6, v[48:49]
	v_lshl_add_u64 v[34:35], s[12:13], 0, v[34:35]
	s_lshl_b32 s0, s27, 2
	v_lshl_add_u64 v[34:35], v[34:35], 0, s[0:1]
	s_lshl_b32 s0, s64, 2
	v_lshl_add_u64 v[34:35], v[34:35], 0, s[0:1]
	s_waitcnt lgkmcnt(0)
	v_add_f32_e32 v32, v32, v33
	global_store_dword v[34:35], v32, off sc1
; __device__ __forceinline__ unsigned cvt_pk_bf16(float lo, float hi) { unsigned r; asm volatile("v_cvt_pk_bf16_f32 %0, %1, %2" : "=v"(r) : "v"(lo), "v"(hi)); return r; }
;     __device__ __forceinline__ void operator()(const f32x4 (&acc)[2][2][4][2], const Unit& u, int wr, int wc, int fr, int fq) const {
;     ...
;             for (int m = 0; m < 4; ++m) { const int r = row0 + ai * HALF + m * 16; float ss = 0.f;
; #pragma unroll
;                 for (int bj = 0; bj < 2; ++bj) { const int c = col0 + bj * HALF;
;                     const f32x4 xa = *(const f32x4*)(x + (size_t)r * 1024 + c), xb = *(const f32x4*)(x + (size_t)r * 1024 + c + 4);
;                     const f32x4 v0 = xa + g1v[bj][0] * acc[ai][bj][m][0], v1 = xb + g1v[bj][1] * acc[ai][bj][m][1];
;                     *(f32x4*)(out + (size_t)r * 1024 + c) = v0; *(f32x4*)(out + (size_t)r * 1024 + c + 4) = v1;
;                     ss += (v0[0] * v0[0] + v0[1] * v0[1]) + (v0[2] * v0[2] + v0[3] * v0[3]) + (v1[0] * v1[0] + v1[1] * v1[1]) + (v1[2] * v1[2] + v1[3] * v1[3]);
;                     const f32x4 a0 = v0 * csv[bj][0], a1 = v1 * csv[bj][1];
;                     u32x4 w; w.x = cvt_pk_bf16(a0[0], a0[1]); w.y = cvt_pk_bf16(a0[2], a0[3]); w.z = cvt_pk_bf16(a1[0], a1[1]); w.w = cvt_pk_bf16(a1[2], a1[3]);
;                     *(u32x4*)(a3 + (size_t)r * 1024 + c) = w; }
;                 ss += __shfl_xor(ss, 16); ss += __shfl_xor(ss, 32);
;                 if (fq == 0) rs[(size_t)r * 16 + (u.pn & 3) * 4 + wc] = ss; }
.LBB0_560:
	s_or_b64 exec, exec, s[38:39]
	v_add_u32_e32 v32, 0xa0, v164
	s_waitcnt lgkmcnt(0)
	v_ashrrev_i32_e32 v33, 31, v32
	v_lshlrev_b64 v[42:43], 12, v[32:33]
	v_lshl_add_u64 v[34:35], s[52:53], 0, v[42:43]
	v_lshl_add_u64 v[44:45], v[34:35], 0, v[162:163]
	s_nop 0
	s_nop 0
	v_lshlrev_b64 v[46:47], 11, v[32:33]
	v_lshl_add_u64 v[42:43], s[48:49], 0, v[42:43]
	v_lshl_add_u64 v[46:47], s[10:11], 0, v[46:47]
	v_lshl_add_u64 v[42:43], v[42:43], 0, v[162:163]
	v_lshl_add_u64 v[46:47], v[160:161], 1, v[46:47]
	s_waitcnt vmcnt(5)
	v_pk_fma_f32 v[30:31], v[30:31], v[78:79], v[246:247]
	v_pk_fma_f32 v[28:29], v[28:29], v[76:77], v[244:245]
	s_waitcnt vmcnt(4)
	v_pk_fma_f32 v[26:27], v[26:27], v[74:75], v[250:251]
	v_pk_fma_f32 v[24:25], v[24:25], v[72:73], v[248:249]
	v_add_u32_e32 v253, 0xb0000, v252
	global_load_dwordx4 v[244:247], v253, s[52:53] offset:512
	global_load_dwordx4 v[248:251], v253, s[52:53] offset:528
	v_pk_mul_f32 v[36:37], v[138:139], v[30:31]
	v_pk_mul_f32 v[34:35], v[142:143], v[28:29]
	global_store_dwordx4 v[42:43], v[28:31], off sc1
	global_store_dwordx4 v[42:43], v[24:27], off offset:16 sc1
	v_pk_mul_f32 v[38:39], v[136:137], v[26:27]
	v_pk_mul_f32 v[40:41], v[140:141], v[24:25]
	v_cvt_pk_bf16_f32 v34, v34, v35
	v_cvt_pk_bf16_f32 v35, v36, v37
	v_mul_f32_e32 v29, v29, v29
	v_cvt_pk_bf16_f32 v36, v40, v41
	v_cvt_pk_bf16_f32 v37, v38, v39
	global_store_dwordx4 v[46:47], v[34:37], off sc1
	s_nop 0
	s_nop 0
	v_mul_f32_e32 v31, v31, v31
	v_mul_f32_e32 v25, v25, v25
	v_fmac_f32_e32 v29, v28, v28
	v_fmac_f32_e32 v31, v30, v30
	v_mul_f32_e32 v27, v27, v27
	v_fmac_f32_e32 v25, v24, v24
	v_add_f32_e32 v24, v29, v31
	v_fmac_f32_e32 v27, v26, v26
	v_add_f32_e32 v24, v24, v25
	v_add_f32_e32 v24, v27, v24
	s_waitcnt vmcnt(5)
	v_pk_fma_f32 v[22:23], v[22:23], v[94:95], v[230:231]
	v_pk_fma_f32 v[20:21], v[20:21], v[92:93], v[228:229]
	s_waitcnt vmcnt(4)
	v_pk_fma_f32 v[16:17], v[16:17], v[88:89], v[232:233]
	v_mul_f32_e32 v25, v21, v21
	v_mul_f32_e32 v26, v23, v23
	v_pk_fma_f32 v[18:19], v[18:19], v[90:91], v[234:235]
	v_mul_f32_e32 v27, v17, v17
	v_fmac_f32_e32 v25, v20, v20
	v_fmac_f32_e32 v26, v22, v22
	v_mul_f32_e32 v28, v19, v19
	v_fmac_f32_e32 v27, v16, v16
	v_add_f32_e32 v25, v25, v26
	v_fmac_f32_e32 v28, v18, v18
	v_add_f32_e32 v25, v25, v27
	v_add_f32_e32 v25, v28, v25
	v_add_f32_e32 v28, v24, v25
	ds_bpermute_b32 v29, v182, v28
	global_store_dwordx4 v[42:43], v[20:23], off offset:512 sc1
	global_store_dwordx4 v[42:43], v[16:19], off offset:528 sc1
	v_pk_mul_f32 v[26:27], v[168:169], v[16:17]
	v_pk_mul_f32 v[20:21], v[170:171], v[20:21]
	v_pk_mul_f32 v[22:23], v[172:173], v[22:23]
	s_waitcnt lgkmcnt(0)
	v_add_f32_e32 v16, v28, v29
	ds_bpermute_b32 v17, v130, v16
	v_pk_mul_f32 v[24:25], v[166:167], v[18:19]
	v_cvt_pk_bf16_f32 v18, v20, v21
	v_cvt_pk_bf16_f32 v19, v22, v23
	v_cvt_pk_bf16_f32 v20, v26, v27
	s_nop 0
	v_cvt_pk_bf16_f32 v21, v24, v25
	global_store_dwordx4 v[46:47], v[18:21], off offset:256 sc1
	s_and_saveexec_b64 s[38:39], s[6:7]
	s_cbranch_execz .LBB0_562
	v_lshlrev_b64 v[18:19], 6, v[32:33]
	v_lshl_add_u64 v[18:19], s[12:13], 0, v[18:19]
	s_lshl_b32 s0, s27, 2
	v_lshl_add_u64 v[18:19], v[18:19], 0, s[0:1]
	s_lshl_b32 s0, s64, 2
	v_lshl_add_u64 v[18:19], v[18:19], 0, s[0:1]
	s_waitcnt lgkmcnt(0)
	v_add_f32_e32 v16, v16, v17
	global_store_dword v[18:19], v16, off sc1
.LBB0_562:
	s_or_b64 exec, exec, s[38:39]
	v_add_u32_e32 v16, 0xb0, v164
	s_waitcnt lgkmcnt(0)
	v_ashrrev_i32_e32 v17, 31, v16
	v_lshlrev_b64 v[26:27], 12, v[16:17]
	v_lshl_add_u64 v[18:19], s[52:53], 0, v[26:27]
	v_lshl_add_u64 v[28:29], v[18:19], 0, v[162:163]
	s_nop 0
	s_nop 0
	v_lshlrev_b64 v[30:31], 11, v[16:17]
	v_lshl_add_u64 v[26:27], s[48:49], 0, v[26:27]
	v_lshl_add_u64 v[30:31], s[10:11], 0, v[30:31]
	v_lshl_add_u64 v[26:27], v[26:27], 0, v[162:163]
	v_lshl_add_u64 v[30:31], v[160:161], 1, v[30:31]
	s_waitcnt vmcnt(3)
	v_pk_fma_f32 v[14:15], v[14:15], v[78:79], v[238:239]
	v_pk_fma_f32 v[12:13], v[12:13], v[76:77], v[236:237]
	s_waitcnt vmcnt(2)
	v_pk_fma_f32 v[10:11], v[10:11], v[74:75], v[242:243]
	v_pk_fma_f32 v[8:9], v[8:9], v[72:73], v[240:241]
	v_pk_mul_f32 v[20:21], v[138:139], v[14:15]
	v_pk_mul_f32 v[18:19], v[142:143], v[12:13]
	global_store_dwordx4 v[26:27], v[12:15], off sc1
	global_store_dwordx4 v[26:27], v[8:11], off offset:16 sc1
	v_pk_mul_f32 v[22:23], v[136:137], v[10:11]
	v_pk_mul_f32 v[24:25], v[140:141], v[8:9]
	v_cvt_pk_bf16_f32 v18, v18, v19
	v_cvt_pk_bf16_f32 v19, v20, v21
	v_mul_f32_e32 v13, v13, v13
	v_cvt_pk_bf16_f32 v20, v24, v25
	v_cvt_pk_bf16_f32 v21, v22, v23
	global_store_dwordx4 v[30:31], v[18:21], off sc1
	s_nop 0
	s_nop 0
	v_mul_f32_e32 v15, v15, v15
	v_mul_f32_e32 v9, v9, v9
	v_fmac_f32_e32 v13, v12, v12
	v_fmac_f32_e32 v15, v14, v14
	v_mul_f32_e32 v11, v11, v11
	v_fmac_f32_e32 v9, v8, v8
	v_add_f32_e32 v8, v13, v15
	v_fmac_f32_e32 v11, v10, v10
	v_add_f32_e32 v8, v8, v9
	v_add_f32_e32 v8, v11, v8
	s_waitcnt vmcnt(1)
	v_pk_fma_f32 v[6:7], v[6:7], v[94:95], v[246:247]
	v_pk_fma_f32 v[4:5], v[4:5], v[92:93], v[244:245]
	s_waitcnt vmcnt(0)
	v_pk_fma_f32 v[0:1], v[0:1], v[88:89], v[248:249]
	v_mul_f32_e32 v9, v5, v5
	v_mul_f32_e32 v10, v7, v7
	v_pk_fma_f32 v[2:3], v[2:3], v[90:91], v[250:251]
	v_mul_f32_e32 v11, v1, v1
	v_fmac_f32_e32 v9, v4, v4
	v_fmac_f32_e32 v10, v6, v6
	v_mul_f32_e32 v12, v3, v3
	v_fmac_f32_e32 v11, v0, v0
	v_add_f32_e32 v9, v9, v10
	v_fmac_f32_e32 v12, v2, v2
	v_add_f32_e32 v9, v9, v11
	v_add_f32_e32 v9, v12, v9
	v_add_f32_e32 v12, v8, v9
	ds_bpermute_b32 v13, v182, v12
	global_store_dwordx4 v[26:27], v[4:7], off offset:512 sc1
	global_store_dwordx4 v[26:27], v[0:3], off offset:528 sc1
	v_pk_mul_f32 v[10:11], v[168:169], v[0:1]
	v_pk_mul_f32 v[4:5], v[170:171], v[4:5]
	v_pk_mul_f32 v[6:7], v[172:173], v[6:7]
	s_waitcnt lgkmcnt(0)
	v_add_f32_e32 v0, v12, v13
	ds_bpermute_b32 v1, v130, v0
	v_pk_mul_f32 v[8:9], v[166:167], v[2:3]
	v_cvt_pk_bf16_f32 v2, v4, v5
	v_cvt_pk_bf16_f32 v3, v6, v7
	v_cvt_pk_bf16_f32 v4, v10, v11
	s_nop 0
	v_cvt_pk_bf16_f32 v5, v8, v9
	global_store_dwordx4 v[30:31], v[2:5], off offset:256 sc1
	s_and_saveexec_b64 s[38:39], s[6:7]
	s_cbranch_execz .LBB0_564
	v_lshlrev_b64 v[2:3], 6, v[16:17]
	v_lshl_add_u64 v[2:3], s[12:13], 0, v[2:3]
	s_lshl_b32 s0, s27, 2
	v_lshl_add_u64 v[2:3], v[2:3], 0, s[0:1]
	s_lshl_b32 s0, s64, 2
	v_lshl_add_u64 v[2:3], v[2:3], 0, s[0:1]
	s_waitcnt lgkmcnt(0)
	v_add_f32_e32 v0, v0, v1
	global_store_dword v[2:3], v0, off sc1

;     static __device__ __forceinline__ unsigned pkh(float a, float b) { return (unsigned)__builtin_bit_cast(unsigned short, (_Float16)a) | ((unsigned)__builtin_bit_cast(unsigned short, (_Float16)b) << 16); }
;     static __device__ __forceinline__ unsigned pkh(float a, float b) { return (unsigned)__builtin_bit_cast(unsigned short, (_Float16)a) | ((unsigned)__builtin_bit_cast(unsigned short, (_Float16)b) << 16); }
;     __device__ __forceinline__ void operator()(const f32x4 (&acc)[2][2][4][2], const Unit& u, int wr, int wc, int fr, int fq) const {
;         const int row0 = u.pm * BM + wr * 64 + fr, col0 = u.pn * BM + wc * 32 + 8 * fq;
;         const float* sbp = sb + (size_t)((u.pm * BM) >> 11) * 2048;
;         f32x4 bv[2][2];
; #pragma unroll
;         for (int bj = 0; bj < 2; ++bj)
; #pragma unroll
;             for (int n = 0; n < 2; ++n) bv[bj][n] = *(const f32x4*)(sbp + col0 + bj * HALF + 4 * n);
; #pragma unroll
;         for (int ai = 0; ai < 2; ++ai)
; #pragma unroll
;             for (int m = 0; m < 4; ++m) { const int r = row0 + ai * HALF + m * 16;
;                 float rstd; { const f32x4 p0 = *(const f32x4*)(rs + (size_t)r * 16), p1 = *(const f32x4*)(rs + (size_t)r * 16 + 4), p2 = *(const f32x4*)(rs + (size_t)r * 16 + 8), p3 = *(const f32x4*)(rs + (size_t)r * 16 + 12);
;                   const f32x4 ps = (p0 + p1) + (p2 + p3); rstd = rsqrtf(((ps[0] + ps[1]) + (ps[2] + ps[3])) * (1.f / 1024.f) + 1e-6f); }
;                 bf16_t* rowp = O + (size_t)r * ldc + col0;
; #pragma unroll
;                 for (int bj = 0; bj < 2; ++bj) { const f32x4 v0 = acc[ai][bj][m][0] * rstd + bv[bj][0], v1 = acc[ai][bj][m][1] * rstd + bv[bj][1];
;                     u32x4 w; w.x = pkh(v0[0], v0[1]); w.y = pkh(v0[2], v0[3]); w.z = pkh(v1[0], v1[1]); w.w = pkh(v1[2], v1[3]);
;                     *(u32x4*)(rowp + bj * HALF) = w; } }
.LBB0_640:
	v_lshl_add_u32 v162, s0, 8, v164
	v_ashrrev_i32_e32 v163, 31, v162
	v_lshlrev_b64 v[96:97], 6, v[162:163]
	v_lshl_add_u64 v[96:97], s[12:13], 0, v[96:97]
	global_load_dwordx4 v[176:179], v[96:97], off
	global_load_dwordx4 v[180:183], v[96:97], off offset:16
	global_load_dwordx4 v[184:187], v[96:97], off offset:32
	global_load_dwordx4 v[188:191], v[96:97], off offset:48
	s_ashr_i32 s0, s0, 3
	v_lshl_or_b32 v160, s1, 8, v166
	s_ashr_i32 s1, s0, 31
	s_lshl_b64 s[0:1], s[0:1], 13
	s_add_u32 s0, s22, s0
	v_ashrrev_i32_e32 v161, 31, v160
	s_addc_u32 s1, s23, s1
	v_lshl_add_u64 v[96:97], v[160:161], 2, s[0:1]
	global_load_dwordx4 v[108:111], v[96:97], off
	global_load_dwordx4 v[104:107], v[96:97], off offset:16
	global_load_dwordx4 v[100:103], v[96:97], off offset:512
	s_nop 0
	global_load_dwordx4 v[96:99], v[96:97], off offset:528
	v_lshlrev_b64 v[192:193], 12, v[162:163]
	v_or_b32_e32 v172, 16, v162
	v_lshlrev_b64 v[160:161], 1, v[160:161]
	v_ashrrev_i32_e32 v173, 31, v172
	v_lshl_add_u64 v[192:193], s[54:55], 0, v[192:193]
	s_waitcnt vmcnt(0)
	v_pk_add_f32 v[178:179], v[178:179], v[182:183]
	v_pk_add_f32 v[176:177], v[176:177], v[180:181]
	v_pk_add_f32 v[180:181], v[186:187], v[190:191]
	v_pk_add_f32 v[182:183], v[184:185], v[188:189]
	v_pk_add_f32 v[178:179], v[178:179], v[180:181]
	v_pk_add_f32 v[176:177], v[176:177], v[182:183]
	s_nop 0
	v_pk_mov_b32 v[180:181], v[176:177], v[178:179] op_sel:[1,0]
	v_mov_b32_e32 v177, v179
	v_pk_add_f32 v[176:177], v[180:181], v[176:177]
	v_lshl_add_u64 v[178:179], v[192:193], 0, v[160:161]
	v_add_f32_e32 v163, v176, v177
	v_fmamk_f32 v163, v163, 0x3a800000, v170
	v_mul_f32_e32 v171, 0x4b800000, v163
	v_cmp_gt_f32_e32 vcc, s62, v163
	v_lshlrev_b64 v[176:177], 6, v[172:173]
	v_lshl_add_u64 v[176:177], s[12:13], 0, v[176:177]
	v_cndmask_b32_e32 v163, v163, v171, vcc
	v_rsq_f32_e32 v163, v163
	v_lshlrev_b64 v[172:173], 12, v[172:173]
	v_mul_f32_e32 v171, 0x45800000, v163
	v_cndmask_b32_e32 v180, v163, v171, vcc
	v_pk_fma_f32 v[142:143], v[142:143], v[180:181], v[110:111] op_sel_hi:[1,0,1]
	v_pk_fma_f32 v[140:141], v[140:141], v[180:181], v[108:109] op_sel_hi:[1,0,1]
	v_pk_fma_f32 v[138:139], v[138:139], v[180:181], v[106:107] op_sel_hi:[1,0,1]
	v_pk_fma_f32 v[136:137], v[136:137], v[180:181], v[104:105] op_sel_hi:[1,0,1]
	v_pk_fma_f32 v[134:135], v[134:135], v[180:181], v[102:103] op_sel_hi:[1,0,1]
	v_pk_fma_f32 v[132:133], v[132:133], v[180:181], v[100:101] op_sel_hi:[1,0,1]
	v_pk_fma_f32 v[130:131], v[130:131], v[180:181], v[98:99] op_sel_hi:[1,0,1]
	v_pk_fma_f32 v[128:129], v[128:129], v[180:181], v[96:97] op_sel_hi:[1,0,1]
	v_cvt_f16_f32_e32 v140, v140
	v_cvt_f16_f32_sdwa v141, v141 dst_sel:WORD_1 dst_unused:UNUSED_PAD src0_sel:DWORD
	v_cvt_f16_f32_e32 v142, v142
	v_cvt_f16_f32_sdwa v143, v143 dst_sel:WORD_1 dst_unused:UNUSED_PAD src0_sel:DWORD
	v_cvt_f16_f32_e32 v136, v136
	v_cvt_f16_f32_sdwa v137, v137 dst_sel:WORD_1 dst_unused:UNUSED_PAD src0_sel:DWORD
	v_cvt_f16_f32_e32 v138, v138
	v_cvt_f16_f32_sdwa v139, v139 dst_sel:WORD_1 dst_unused:UNUSED_PAD src0_sel:DWORD
	v_cvt_f16_f32_e32 v132, v132
	v_cvt_f16_f32_sdwa v133, v133 dst_sel:WORD_1 dst_unused:UNUSED_PAD src0_sel:DWORD
	v_cvt_f16_f32_e32 v134, v134
	v_cvt_f16_f32_sdwa v135, v135 dst_sel:WORD_1 dst_unused:UNUSED_PAD src0_sel:DWORD
	v_cvt_f16_f32_e32 v163, v128
	v_cvt_f16_f32_sdwa v171, v129 dst_sel:WORD_1 dst_unused:UNUSED_PAD src0_sel:DWORD
	v_cvt_f16_f32_e32 v175, v130
	v_cvt_f16_f32_sdwa v180, v131 dst_sel:WORD_1 dst_unused:UNUSED_PAD src0_sel:DWORD
	v_or_b32_e32 v128, v141, v140
	v_or_b32_e32 v129, v143, v142
	v_or_b32_e32 v130, v137, v136
	v_or_b32_e32 v131, v139, v138
	v_or_b32_e32 v132, v133, v132
	v_or_b32_e32 v133, v135, v134
	v_or_b32_e32 v134, v171, v163
	v_or_b32_e32 v135, v180, v175
	global_store_dwordx4 v[178:179], v[128:131], off sc1
	global_store_dwordx4 v[178:179], v[132:135], off offset:256 sc1
	global_load_dwordx4 v[128:131], v[176:177], off
	s_nop 0
	global_load_dwordx4 v[132:135], v[176:177], off offset:16
	global_load_dwordx4 v[136:139], v[176:177], off offset:32
	global_load_dwordx4 v[140:143], v[176:177], off offset:48
	v_or_b32_e32 v176, 32, v162
	v_ashrrev_i32_e32 v177, 31, v176
	v_lshlrev_b64 v[178:179], 6, v[176:177]
	s_waitcnt vmcnt(2)
	v_pk_add_f32 v[130:131], v[130:131], v[134:135]
	v_pk_add_f32 v[128:129], v[128:129], v[132:133]
	s_waitcnt vmcnt(0)
;     static __device__ __forceinline__ unsigned pkh(float a, float b) { return (unsigned)__builtin_bit_cast(unsigned short, (_Float16)a) | ((unsigned)__builtin_bit_cast(unsigned short, (_Float16)b) << 16); }
;     static __device__ __forceinline__ unsigned pkh(float a, float b) { return (unsigned)__builtin_bit_cast(unsigned short, (_Float16)a) | ((unsigned)__builtin_bit_cast(unsigned short, (_Float16)b) << 16); }
;     __device__ __forceinline__ void operator()(const f32x4 (&acc)[2][2][4][2], const Unit& u, int wr, int wc, int fr, int fq) const {
;     ...
;         for (int ai = 0; ai < 2; ++ai)
; #pragma unroll
;             for (int m = 0; m < 4; ++m) { const int r = row0 + ai * HALF + m * 16;
;                 float rstd; { const f32x4 p0 = *(const f32x4*)(rs + (size_t)r * 16), p1 = *(const f32x4*)(rs + (size_t)r * 16 + 4), p2 = *(const f32x4*)(rs + (size_t)r * 16 + 8), p3 = *(const f32x4*)(rs + (size_t)r * 16 + 12);
;                   const f32x4 ps = (p0 + p1) + (p2 + p3); rstd = rsqrtf(((ps[0] + ps[1]) + (ps[2] + ps[3])) * (1.f / 1024.f) + 1e-6f); }
;                 bf16_t* rowp = O + (size_t)r * ldc + col0;
; #pragma unroll
;                 for (int bj = 0; bj < 2; ++bj) { const f32x4 v0 = acc[ai][bj][m][0] * rstd + bv[bj][0], v1 = acc[ai][bj][m][1] * rstd + bv[bj][1];
;                     u32x4 w; w.x = pkh(v0[0], v0[1]); w.y = pkh(v0[2], v0[3]); w.z = pkh(v1[0], v1[1]); w.w = pkh(v1[2], v1[3]);
;                     *(u32x4*)(rowp + bj * HALF) = w; } }
	v_pk_add_f32 v[132:133], v[138:139], v[142:143]
	v_pk_add_f32 v[134:135], v[136:137], v[140:141]
	v_pk_add_f32 v[130:131], v[130:131], v[132:133]
	v_pk_add_f32 v[128:129], v[128:129], v[134:135]
	s_nop 0
	v_pk_mov_b32 v[132:133], v[128:129], v[130:131] op_sel:[1,0]
	v_mov_b32_e32 v129, v131
	v_pk_add_f32 v[128:129], v[132:133], v[128:129]
	v_lshl_add_u64 v[130:131], s[12:13], 0, v[178:179]
	v_add_f32_e32 v128, v128, v129
	v_fmamk_f32 v128, v128, 0x3a800000, v170
	v_mul_f32_e32 v129, 0x4b800000, v128
	v_cmp_gt_f32_e32 vcc, s62, v128
	s_nop 1
	v_cndmask_b32_e32 v128, v128, v129, vcc
	v_rsq_f32_e32 v132, v128
	v_lshl_add_u64 v[128:129], s[54:55], 0, v[172:173]
	v_lshl_add_u64 v[128:129], v[128:129], 0, v[160:161]
	v_mul_f32_e32 v133, 0x45800000, v132
	v_cndmask_b32_e32 v132, v132, v133, vcc
	v_pk_fma_f32 v[126:127], v[126:127], v[132:133], v[110:111] op_sel_hi:[1,0,1]
	v_pk_fma_f32 v[124:125], v[124:125], v[132:133], v[108:109] op_sel_hi:[1,0,1]
	v_pk_fma_f32 v[122:123], v[122:123], v[132:133], v[106:107] op_sel_hi:[1,0,1]
	v_pk_fma_f32 v[120:121], v[120:121], v[132:133], v[104:105] op_sel_hi:[1,0,1]
	v_pk_fma_f32 v[118:119], v[118:119], v[132:133], v[102:103] op_sel_hi:[1,0,1]
	v_pk_fma_f32 v[116:117], v[116:117], v[132:133], v[100:101] op_sel_hi:[1,0,1]
	v_pk_fma_f32 v[114:115], v[114:115], v[132:133], v[98:99] op_sel_hi:[1,0,1]
	v_pk_fma_f32 v[112:113], v[112:113], v[132:133], v[96:97] op_sel_hi:[1,0,1]
	v_cvt_f16_f32_e32 v124, v124
	v_cvt_f16_f32_sdwa v125, v125 dst_sel:WORD_1 dst_unused:UNUSED_PAD src0_sel:DWORD
	v_cvt_f16_f32_e32 v126, v126
	v_cvt_f16_f32_sdwa v127, v127 dst_sel:WORD_1 dst_unused:UNUSED_PAD src0_sel:DWORD
	v_cvt_f16_f32_e32 v120, v120
	v_cvt_f16_f32_sdwa v121, v121 dst_sel:WORD_1 dst_unused:UNUSED_PAD src0_sel:DWORD
	v_cvt_f16_f32_e32 v122, v122
	v_cvt_f16_f32_sdwa v123, v123 dst_sel:WORD_1 dst_unused:UNUSED_PAD src0_sel:DWORD
	v_cvt_f16_f32_e32 v116, v116
	v_cvt_f16_f32_sdwa v117, v117 dst_sel:WORD_1 dst_unused:UNUSED_PAD src0_sel:DWORD
	v_cvt_f16_f32_e32 v118, v118
	v_cvt_f16_f32_sdwa v119, v119 dst_sel:WORD_1 dst_unused:UNUSED_PAD src0_sel:DWORD
	v_cvt_f16_f32_e32 v132, v112
	v_cvt_f16_f32_sdwa v133, v113 dst_sel:WORD_1 dst_unused:UNUSED_PAD src0_sel:DWORD
	v_cvt_f16_f32_e32 v134, v114
	v_cvt_f16_f32_sdwa v135, v115 dst_sel:WORD_1 dst_unused:UNUSED_PAD src0_sel:DWORD
	v_or_b32_e32 v112, v125, v124
	v_or_b32_e32 v113, v127, v126
	v_or_b32_e32 v114, v121, v120
	v_or_b32_e32 v115, v123, v122
	v_or_b32_e32 v116, v117, v116
	v_or_b32_e32 v117, v119, v118
	v_or_b32_e32 v118, v133, v132
	v_or_b32_e32 v119, v135, v134
	global_store_dwordx4 v[128:129], v[112:115], off sc1
	global_store_dwordx4 v[128:129], v[116:119], off offset:256 sc1
	global_load_dwordx4 v[112:115], v[130:131], off
	s_nop 0
	global_load_dwordx4 v[116:119], v[130:131], off offset:16
	global_load_dwordx4 v[120:123], v[130:131], off offset:32
	global_load_dwordx4 v[124:127], v[130:131], off offset:48
	v_or_b32_e32 v128, 48, v162
	v_lshlrev_b64 v[130:131], 12, v[176:177]
	v_ashrrev_i32_e32 v129, 31, v128
	v_lshlrev_b64 v[132:133], 6, v[128:129]
	s_waitcnt vmcnt(2)
	v_pk_add_f32 v[114:115], v[114:115], v[118:119]
	v_pk_add_f32 v[112:113], v[112:113], v[116:117]
	s_waitcnt vmcnt(0)
	v_pk_add_f32 v[116:117], v[122:123], v[126:127]
	v_pk_add_f32 v[118:119], v[120:121], v[124:125]
	v_pk_add_f32 v[114:115], v[114:115], v[116:117]
	v_pk_add_f32 v[112:113], v[112:113], v[118:119]
	s_nop 0
	v_pk_mov_b32 v[116:117], v[112:113], v[114:115] op_sel:[1,0]
	v_mov_b32_e32 v113, v115
	v_pk_add_f32 v[112:113], v[116:117], v[112:113]
	v_lshl_add_u64 v[114:115], s[12:13], 0, v[132:133]
	v_add_f32_e32 v112, v112, v113
	v_fmamk_f32 v112, v112, 0x3a800000, v170
	v_mul_f32_e32 v113, 0x4b800000, v112
	v_cmp_gt_f32_e32 vcc, s62, v112
	s_nop 1
	v_cndmask_b32_e32 v112, v112, v113, vcc
	v_rsq_f32_e32 v116, v112
	v_lshl_add_u64 v[112:113], s[54:55], 0, v[130:131]
	v_lshl_add_u64 v[112:113], v[112:113], 0, v[160:161]
	v_mul_f32_e32 v117, 0x45800000, v116
	v_cndmask_b32_e32 v116, v116, v117, vcc
	v_pk_fma_f32 v[94:95], v[94:95], v[116:117], v[110:111] op_sel_hi:[1,0,1]
	v_pk_fma_f32 v[92:93], v[92:93], v[116:117], v[108:109] op_sel_hi:[1,0,1]
	v_pk_fma_f32 v[90:91], v[90:91], v[116:117], v[106:107] op_sel_hi:[1,0,1]
	v_pk_fma_f32 v[88:89], v[88:89], v[116:117], v[104:105] op_sel_hi:[1,0,1]
	v_pk_fma_f32 v[86:87], v[86:87], v[116:117], v[102:103] op_sel_hi:[1,0,1]
	v_pk_fma_f32 v[84:85], v[84:85], v[116:117], v[100:101] op_sel_hi:[1,0,1]
	v_pk_fma_f32 v[82:83], v[82:83], v[116:117], v[98:99] op_sel_hi:[1,0,1]
	v_pk_fma_f32 v[80:81], v[80:81], v[116:117], v[96:97] op_sel_hi:[1,0,1]
	v_cvt_f16_f32_e32 v92, v92
	v_cvt_f16_f32_sdwa v93, v93 dst_sel:WORD_1 dst_unused:UNUSED_PAD src0_sel:DWORD
	v_cvt_f16_f32_e32 v94, v94
	v_cvt_f16_f32_sdwa v95, v95 dst_sel:WORD_1 dst_unused:UNUSED_PAD src0_sel:DWORD
	v_cvt_f16_f32_e32 v88, v88
	v_cvt_f16_f32_sdwa v89, v89 dst_sel:WORD_1 dst_unused:UNUSED_PAD src0_sel:DWORD
	v_cvt_f16_f32_e32 v90, v90
	v_cvt_f16_f32_sdwa v91, v91 dst_sel:WORD_1 dst_unused:UNUSED_PAD src0_sel:DWORD
	v_cvt_f16_f32_e32 v84, v84
	v_cvt_f16_f32_sdwa v85, v85 dst_sel:WORD_1 dst_unused:UNUSED_PAD src0_sel:DWORD
	v_cvt_f16_f32_e32 v86, v86
	v_cvt_f16_f32_sdwa v87, v87 dst_sel:WORD_1 dst_unused:UNUSED_PAD src0_sel:DWORD
	v_cvt_f16_f32_e32 v116, v80
	v_cvt_f16_f32_sdwa v117, v81 dst_sel:WORD_1 dst_unused:UNUSED_PAD src0_sel:DWORD
	v_cvt_f16_f32_e32 v118, v82
	v_cvt_f16_f32_sdwa v119, v83 dst_sel:WORD_1 dst_unused:UNUSED_PAD src0_sel:DWORD
	v_or_b32_e32 v80, v93, v92
	v_or_b32_e32 v81, v95, v94
	v_or_b32_e32 v82, v89, v88
	v_or_b32_e32 v83, v91, v90
	v_or_b32_e32 v84, v85, v84
	v_or_b32_e32 v85, v87, v86
	v_or_b32_e32 v86, v117, v116
	v_or_b32_e32 v87, v119, v118
	global_store_dwordx4 v[112:113], v[80:83], off sc1
	global_store_dwordx4 v[112:113], v[84:87], off offset:256 sc1
	global_load_dwordx4 v[80:83], v[114:115], off
	s_nop 0
	global_load_dwordx4 v[84:87], v[114:115], off offset:16
	global_load_dwordx4 v[88:91], v[114:115], off offset:32
	global_load_dwordx4 v[92:95], v[114:115], off offset:48
	v_add_u32_e32 v112, 0x80, v162
	v_lshlrev_b64 v[114:115], 12, v[128:129]
	v_ashrrev_i32_e32 v113, 31, v112
	v_lshlrev_b64 v[116:117], 6, v[112:113]
	s_waitcnt vmcnt(2)
;     static __device__ __forceinline__ unsigned pkh(float a, float b) { return (unsigned)__builtin_bit_cast(unsigned short, (_Float16)a) | ((unsigned)__builtin_bit_cast(unsigned short, (_Float16)b) << 16); }
;     static __device__ __forceinline__ unsigned pkh(float a, float b) { return (unsigned)__builtin_bit_cast(unsigned short, (_Float16)a) | ((unsigned)__builtin_bit_cast(unsigned short, (_Float16)b) << 16); }
;     __device__ __forceinline__ void operator()(const f32x4 (&acc)[2][2][4][2], const Unit& u, int wr, int wc, int fr, int fq) const {
;     ...
;             for (int m = 0; m < 4; ++m) { const int r = row0 + ai * HALF + m * 16;
;                 float rstd; { const f32x4 p0 = *(const f32x4*)(rs + (size_t)r * 16), p1 = *(const f32x4*)(rs + (size_t)r * 16 + 4), p2 = *(const f32x4*)(rs + (size_t)r * 16 + 8), p3 = *(const f32x4*)(rs + (size_t)r * 16 + 12);
;                   const f32x4 ps = (p0 + p1) + (p2 + p3); rstd = rsqrtf(((ps[0] + ps[1]) + (ps[2] + ps[3])) * (1.f / 1024.f) + 1e-6f); }
;                 bf16_t* rowp = O + (size_t)r * ldc + col0;
; #pragma unroll
;                 for (int bj = 0; bj < 2; ++bj) { const f32x4 v0 = acc[ai][bj][m][0] * rstd + bv[bj][0], v1 = acc[ai][bj][m][1] * rstd + bv[bj][1];
;                     u32x4 w; w.x = pkh(v0[0], v0[1]); w.y = pkh(v0[2], v0[3]); w.z = pkh(v1[0], v1[1]); w.w = pkh(v1[2], v1[3]);
;                     *(u32x4*)(rowp + bj * HALF) = w; } }
	v_pk_add_f32 v[82:83], v[82:83], v[86:87]
	v_pk_add_f32 v[80:81], v[80:81], v[84:85]
	s_waitcnt vmcnt(0)
	v_pk_add_f32 v[84:85], v[90:91], v[94:95]
	v_pk_add_f32 v[86:87], v[88:89], v[92:93]
	v_pk_add_f32 v[82:83], v[82:83], v[84:85]
	v_pk_add_f32 v[80:81], v[80:81], v[86:87]
	s_nop 0
	v_pk_mov_b32 v[84:85], v[80:81], v[82:83] op_sel:[1,0]
	v_mov_b32_e32 v81, v83
	v_pk_add_f32 v[80:81], v[84:85], v[80:81]
	v_lshl_add_u64 v[82:83], s[12:13], 0, v[116:117]
	v_add_f32_e32 v80, v80, v81
	v_fmamk_f32 v80, v80, 0x3a800000, v170
	v_mul_f32_e32 v81, 0x4b800000, v80
	v_cmp_gt_f32_e32 vcc, s62, v80
	s_nop 1
	v_cndmask_b32_e32 v80, v80, v81, vcc
	v_rsq_f32_e32 v84, v80
	v_lshl_add_u64 v[80:81], s[54:55], 0, v[114:115]
	v_lshl_add_u64 v[80:81], v[80:81], 0, v[160:161]
	v_mul_f32_e32 v85, 0x45800000, v84
	v_cndmask_b32_e32 v84, v84, v85, vcc
	v_pk_fma_f32 v[78:79], v[78:79], v[84:85], v[110:111] op_sel_hi:[1,0,1]
	v_pk_fma_f32 v[76:77], v[76:77], v[84:85], v[108:109] op_sel_hi:[1,0,1]
	v_pk_fma_f32 v[74:75], v[74:75], v[84:85], v[106:107] op_sel_hi:[1,0,1]
	v_pk_fma_f32 v[72:73], v[72:73], v[84:85], v[104:105] op_sel_hi:[1,0,1]
	v_pk_fma_f32 v[70:71], v[70:71], v[84:85], v[102:103] op_sel_hi:[1,0,1]
	v_pk_fma_f32 v[68:69], v[68:69], v[84:85], v[100:101] op_sel_hi:[1,0,1]
	v_pk_fma_f32 v[66:67], v[66:67], v[84:85], v[98:99] op_sel_hi:[1,0,1]
	v_pk_fma_f32 v[64:65], v[64:65], v[84:85], v[96:97] op_sel_hi:[1,0,1]
	v_cvt_f16_f32_e32 v76, v76
	v_cvt_f16_f32_sdwa v77, v77 dst_sel:WORD_1 dst_unused:UNUSED_PAD src0_sel:DWORD
	v_cvt_f16_f32_e32 v78, v78
	v_cvt_f16_f32_sdwa v79, v79 dst_sel:WORD_1 dst_unused:UNUSED_PAD src0_sel:DWORD
	v_cvt_f16_f32_e32 v72, v72
	v_cvt_f16_f32_sdwa v73, v73 dst_sel:WORD_1 dst_unused:UNUSED_PAD src0_sel:DWORD
	v_cvt_f16_f32_e32 v74, v74
	v_cvt_f16_f32_sdwa v75, v75 dst_sel:WORD_1 dst_unused:UNUSED_PAD src0_sel:DWORD
	v_cvt_f16_f32_e32 v68, v68
	v_cvt_f16_f32_sdwa v69, v69 dst_sel:WORD_1 dst_unused:UNUSED_PAD src0_sel:DWORD
	v_cvt_f16_f32_e32 v70, v70
	v_cvt_f16_f32_sdwa v71, v71 dst_sel:WORD_1 dst_unused:UNUSED_PAD src0_sel:DWORD
	v_cvt_f16_f32_e32 v84, v64
	v_cvt_f16_f32_sdwa v85, v65 dst_sel:WORD_1 dst_unused:UNUSED_PAD src0_sel:DWORD
	v_cvt_f16_f32_e32 v86, v66
	v_cvt_f16_f32_sdwa v87, v67 dst_sel:WORD_1 dst_unused:UNUSED_PAD src0_sel:DWORD
	v_or_b32_e32 v64, v77, v76
	v_or_b32_e32 v65, v79, v78
	v_or_b32_e32 v66, v73, v72
	v_or_b32_e32 v67, v75, v74
	v_or_b32_e32 v68, v69, v68
	v_or_b32_e32 v69, v71, v70
	v_or_b32_e32 v70, v85, v84
	v_or_b32_e32 v71, v87, v86
	global_store_dwordx4 v[80:81], v[64:67], off sc1
	global_store_dwordx4 v[80:81], v[68:71], off offset:256 sc1
	global_load_dwordx4 v[64:67], v[82:83], off
	s_nop 0
	global_load_dwordx4 v[68:71], v[82:83], off offset:16
	global_load_dwordx4 v[72:75], v[82:83], off offset:32
	global_load_dwordx4 v[76:79], v[82:83], off offset:48
	v_add_u32_e32 v80, 0x90, v162
	v_lshlrev_b64 v[82:83], 12, v[112:113]
	v_ashrrev_i32_e32 v81, 31, v80
	v_lshlrev_b64 v[84:85], 6, v[80:81]
	s_waitcnt vmcnt(2)
	v_pk_add_f32 v[66:67], v[66:67], v[70:71]
	v_pk_add_f32 v[64:65], v[64:65], v[68:69]
	s_waitcnt vmcnt(0)
	v_pk_add_f32 v[68:69], v[74:75], v[78:79]
	v_pk_add_f32 v[70:71], v[72:73], v[76:77]
	v_pk_add_f32 v[66:67], v[66:67], v[68:69]
	v_pk_add_f32 v[64:65], v[64:65], v[70:71]
	s_nop 0
	v_pk_mov_b32 v[68:69], v[64:65], v[66:67] op_sel:[1,0]
	v_mov_b32_e32 v65, v67
	v_pk_add_f32 v[64:65], v[68:69], v[64:65]
	v_lshl_add_u64 v[66:67], s[12:13], 0, v[84:85]
	v_add_f32_e32 v64, v64, v65
	v_fmamk_f32 v64, v64, 0x3a800000, v170
	v_mul_f32_e32 v65, 0x4b800000, v64
	v_cmp_gt_f32_e32 vcc, s62, v64
	s_nop 1
	v_cndmask_b32_e32 v64, v64, v65, vcc
	v_rsq_f32_e32 v68, v64
	v_lshl_add_u64 v[64:65], s[54:55], 0, v[82:83]
	v_lshl_add_u64 v[64:65], v[64:65], 0, v[160:161]
	v_mul_f32_e32 v69, 0x45800000, v68
	v_cndmask_b32_e32 v68, v68, v69, vcc
	v_pk_fma_f32 v[62:63], v[62:63], v[68:69], v[110:111] op_sel_hi:[1,0,1]
	v_pk_fma_f32 v[60:61], v[60:61], v[68:69], v[108:109] op_sel_hi:[1,0,1]
	v_pk_fma_f32 v[58:59], v[58:59], v[68:69], v[106:107] op_sel_hi:[1,0,1]
	v_pk_fma_f32 v[56:57], v[56:57], v[68:69], v[104:105] op_sel_hi:[1,0,1]
	v_pk_fma_f32 v[54:55], v[54:55], v[68:69], v[102:103] op_sel_hi:[1,0,1]
	v_pk_fma_f32 v[52:53], v[52:53], v[68:69], v[100:101] op_sel_hi:[1,0,1]
	v_pk_fma_f32 v[50:51], v[50:51], v[68:69], v[98:99] op_sel_hi:[1,0,1]
	v_pk_fma_f32 v[48:49], v[48:49], v[68:69], v[96:97] op_sel_hi:[1,0,1]
	v_cvt_f16_f32_e32 v60, v60
	v_cvt_f16_f32_sdwa v61, v61 dst_sel:WORD_1 dst_unused:UNUSED_PAD src0_sel:DWORD
	v_cvt_f16_f32_e32 v62, v62
	v_cvt_f16_f32_sdwa v63, v63 dst_sel:WORD_1 dst_unused:UNUSED_PAD src0_sel:DWORD
	v_cvt_f16_f32_e32 v56, v56
	v_cvt_f16_f32_sdwa v57, v57 dst_sel:WORD_1 dst_unused:UNUSED_PAD src0_sel:DWORD
	v_cvt_f16_f32_e32 v58, v58
	v_cvt_f16_f32_sdwa v59, v59 dst_sel:WORD_1 dst_unused:UNUSED_PAD src0_sel:DWORD
	v_cvt_f16_f32_e32 v52, v52
	v_cvt_f16_f32_sdwa v53, v53 dst_sel:WORD_1 dst_unused:UNUSED_PAD src0_sel:DWORD
	v_cvt_f16_f32_e32 v54, v54
	v_cvt_f16_f32_sdwa v55, v55 dst_sel:WORD_1 dst_unused:UNUSED_PAD src0_sel:DWORD
	v_cvt_f16_f32_e32 v68, v48
	v_cvt_f16_f32_sdwa v69, v49 dst_sel:WORD_1 dst_unused:UNUSED_PAD src0_sel:DWORD
	v_cvt_f16_f32_e32 v70, v50
	v_cvt_f16_f32_sdwa v71, v51 dst_sel:WORD_1 dst_unused:UNUSED_PAD src0_sel:DWORD
	v_or_b32_e32 v48, v61, v60
	v_or_b32_e32 v49, v63, v62
	v_or_b32_e32 v50, v57, v56
	v_or_b32_e32 v51, v59, v58
	v_or_b32_e32 v52, v53, v52
	v_or_b32_e32 v53, v55, v54
	v_or_b32_e32 v54, v69, v68
	v_or_b32_e32 v55, v71, v70
	global_store_dwordx4 v[64:65], v[48:51], off sc1
	global_store_dwordx4 v[64:65], v[52:55], off offset:256 sc1
	global_load_dwordx4 v[48:51], v[66:67], off
	s_nop 0
	global_load_dwordx4 v[52:55], v[66:67], off offset:16
	global_load_dwordx4 v[56:59], v[66:67], off offset:32
	global_load_dwordx4 v[60:63], v[66:67], off offset:48
	v_add_u32_e32 v64, 0xa0, v162
	v_lshlrev_b64 v[66:67], 12, v[80:81]
	v_ashrrev_i32_e32 v65, 31, v64
	v_lshlrev_b64 v[68:69], 6, v[64:65]
	s_waitcnt vmcnt(2)
;     static __device__ __forceinline__ unsigned pkh(float a, float b) { return (unsigned)__builtin_bit_cast(unsigned short, (_Float16)a) | ((unsigned)__builtin_bit_cast(unsigned short, (_Float16)b) << 16); }
;     static __device__ __forceinline__ unsigned pkh(float a, float b) { return (unsigned)__builtin_bit_cast(unsigned short, (_Float16)a) | ((unsigned)__builtin_bit_cast(unsigned short, (_Float16)b) << 16); }
;     __device__ __forceinline__ void operator()(const f32x4 (&acc)[2][2][4][2], const Unit& u, int wr, int wc, int fr, int fq) const {
;     ...
;             for (int m = 0; m < 4; ++m) { const int r = row0 + ai * HALF + m * 16;
;                 float rstd; { const f32x4 p0 = *(const f32x4*)(rs + (size_t)r * 16), p1 = *(const f32x4*)(rs + (size_t)r * 16 + 4), p2 = *(const f32x4*)(rs + (size_t)r * 16 + 8), p3 = *(const f32x4*)(rs + (size_t)r * 16 + 12);
;                   const f32x4 ps = (p0 + p1) + (p2 + p3); rstd = rsqrtf(((ps[0] + ps[1]) + (ps[2] + ps[3])) * (1.f / 1024.f) + 1e-6f); }
;                 bf16_t* rowp = O + (size_t)r * ldc + col0;
; #pragma unroll
;                 for (int bj = 0; bj < 2; ++bj) { const f32x4 v0 = acc[ai][bj][m][0] * rstd + bv[bj][0], v1 = acc[ai][bj][m][1] * rstd + bv[bj][1];
;                     u32x4 w; w.x = pkh(v0[0], v0[1]); w.y = pkh(v0[2], v0[3]); w.z = pkh(v1[0], v1[1]); w.w = pkh(v1[2], v1[3]);
;                     *(u32x4*)(rowp + bj * HALF) = w; } }
	v_pk_add_f32 v[50:51], v[50:51], v[54:55]
	v_pk_add_f32 v[48:49], v[48:49], v[52:53]
	s_waitcnt vmcnt(0)
	v_pk_add_f32 v[52:53], v[58:59], v[62:63]
	v_pk_add_f32 v[54:55], v[56:57], v[60:61]
	v_pk_add_f32 v[50:51], v[50:51], v[52:53]
	v_pk_add_f32 v[48:49], v[48:49], v[54:55]
	s_nop 0
	v_pk_mov_b32 v[52:53], v[48:49], v[50:51] op_sel:[1,0]
	v_mov_b32_e32 v49, v51
	v_pk_add_f32 v[48:49], v[52:53], v[48:49]
	v_lshl_add_u64 v[50:51], s[12:13], 0, v[68:69]
	v_add_f32_e32 v48, v48, v49
	v_fmamk_f32 v48, v48, 0x3a800000, v170
	v_mul_f32_e32 v49, 0x4b800000, v48
	v_cmp_gt_f32_e32 vcc, s62, v48
	s_nop 1
	v_cndmask_b32_e32 v48, v48, v49, vcc
	v_rsq_f32_e32 v52, v48
	v_lshl_add_u64 v[48:49], s[54:55], 0, v[66:67]
	v_lshl_add_u64 v[48:49], v[48:49], 0, v[160:161]
	v_mul_f32_e32 v53, 0x45800000, v52
	v_cndmask_b32_e32 v52, v52, v53, vcc
	v_pk_fma_f32 v[46:47], v[46:47], v[52:53], v[110:111] op_sel_hi:[1,0,1]
	v_pk_fma_f32 v[44:45], v[44:45], v[52:53], v[108:109] op_sel_hi:[1,0,1]
	v_pk_fma_f32 v[42:43], v[42:43], v[52:53], v[106:107] op_sel_hi:[1,0,1]
	v_pk_fma_f32 v[40:41], v[40:41], v[52:53], v[104:105] op_sel_hi:[1,0,1]
	v_pk_fma_f32 v[38:39], v[38:39], v[52:53], v[102:103] op_sel_hi:[1,0,1]
	v_pk_fma_f32 v[36:37], v[36:37], v[52:53], v[100:101] op_sel_hi:[1,0,1]
	v_pk_fma_f32 v[34:35], v[34:35], v[52:53], v[98:99] op_sel_hi:[1,0,1]
	v_pk_fma_f32 v[32:33], v[32:33], v[52:53], v[96:97] op_sel_hi:[1,0,1]
	v_cvt_f16_f32_e32 v44, v44
	v_cvt_f16_f32_sdwa v45, v45 dst_sel:WORD_1 dst_unused:UNUSED_PAD src0_sel:DWORD
	v_cvt_f16_f32_e32 v46, v46
	v_cvt_f16_f32_sdwa v47, v47 dst_sel:WORD_1 dst_unused:UNUSED_PAD src0_sel:DWORD
	v_cvt_f16_f32_e32 v40, v40
	v_cvt_f16_f32_sdwa v41, v41 dst_sel:WORD_1 dst_unused:UNUSED_PAD src0_sel:DWORD
	v_cvt_f16_f32_e32 v42, v42
	v_cvt_f16_f32_sdwa v43, v43 dst_sel:WORD_1 dst_unused:UNUSED_PAD src0_sel:DWORD
	v_cvt_f16_f32_e32 v36, v36
	v_cvt_f16_f32_sdwa v37, v37 dst_sel:WORD_1 dst_unused:UNUSED_PAD src0_sel:DWORD
	v_cvt_f16_f32_e32 v38, v38
	v_cvt_f16_f32_sdwa v39, v39 dst_sel:WORD_1 dst_unused:UNUSED_PAD src0_sel:DWORD
	v_cvt_f16_f32_e32 v52, v32
	v_cvt_f16_f32_sdwa v53, v33 dst_sel:WORD_1 dst_unused:UNUSED_PAD src0_sel:DWORD
	v_cvt_f16_f32_e32 v54, v34
	v_cvt_f16_f32_sdwa v55, v35 dst_sel:WORD_1 dst_unused:UNUSED_PAD src0_sel:DWORD
	v_or_b32_e32 v32, v45, v44
	v_or_b32_e32 v33, v47, v46
	v_or_b32_e32 v34, v41, v40
	v_or_b32_e32 v35, v43, v42
	v_or_b32_e32 v36, v37, v36
	v_or_b32_e32 v37, v39, v38
	v_or_b32_e32 v38, v53, v52
	v_or_b32_e32 v39, v55, v54
	global_store_dwordx4 v[48:49], v[32:35], off sc1
	global_store_dwordx4 v[48:49], v[36:39], off offset:256 sc1
	global_load_dwordx4 v[32:35], v[50:51], off
	s_nop 0
	global_load_dwordx4 v[36:39], v[50:51], off offset:16
	global_load_dwordx4 v[40:43], v[50:51], off offset:32
	global_load_dwordx4 v[44:47], v[50:51], off offset:48
	v_add_u32_e32 v48, 0xb0, v162
	v_lshlrev_b64 v[50:51], 12, v[64:65]
	v_ashrrev_i32_e32 v49, 31, v48
	v_lshlrev_b64 v[52:53], 6, v[48:49]
	s_waitcnt vmcnt(2)
	v_pk_add_f32 v[34:35], v[34:35], v[38:39]
	v_pk_add_f32 v[32:33], v[32:33], v[36:37]
	s_waitcnt vmcnt(0)
;     static __device__ __forceinline__ unsigned pkh(float a, float b) { return (unsigned)__builtin_bit_cast(unsigned short, (_Float16)a) | ((unsigned)__builtin_bit_cast(unsigned short, (_Float16)b) << 16); }
;     static __device__ __forceinline__ unsigned pkh(float a, float b) { return (unsigned)__builtin_bit_cast(unsigned short, (_Float16)a) | ((unsigned)__builtin_bit_cast(unsigned short, (_Float16)b) << 16); }
; #define PG8_BAR __builtin_amdgcn_s_barrier()
;     __device__ __forceinline__ void operator()(const f32x4 (&acc)[2][2][4][2], const Unit& u, int wr, int wc, int fr, int fq) const {
;     ...
;             for (int m = 0; m < 4; ++m) { const int r = row0 + ai * HALF + m * 16;
;                 float rstd; { const f32x4 p0 = *(const f32x4*)(rs + (size_t)r * 16), p1 = *(const f32x4*)(rs + (size_t)r * 16 + 4), p2 = *(const f32x4*)(rs + (size_t)r * 16 + 8), p3 = *(const f32x4*)(rs + (size_t)r * 16 + 12);
;                   const f32x4 ps = (p0 + p1) + (p2 + p3); rstd = rsqrtf(((ps[0] + ps[1]) + (ps[2] + ps[3])) * (1.f / 1024.f) + 1e-6f); }
;                 bf16_t* rowp = O + (size_t)r * ldc + col0;
; #pragma unroll
;                 for (int bj = 0; bj < 2; ++bj) { const f32x4 v0 = acc[ai][bj][m][0] * rstd + bv[bj][0], v1 = acc[ai][bj][m][1] * rstd + bv[bj][1];
;                     u32x4 w; w.x = pkh(v0[0], v0[1]); w.y = pkh(v0[2], v0[3]); w.z = pkh(v1[0], v1[1]); w.w = pkh(v1[2], v1[3]);
;                     *(u32x4*)(rowp + bj * HALF) = w; } }
; template <class Epi, class Sched, bool ALIGN_EPI = false, bool SP2 = false>
; __device__ __forceinline__ void gemm_phase(PG8_LAS unsigned char* lds, const Gemm g, const Sched& S, const Epi& E) {
;     ...
;         if constexpr (!Epi::AFTER_DRAIN) { E(acc, cur, wr, wc, fr, fq); S.done(cur); }
;         if (!has_next) break;
; #pragma unroll
;         for (int a = 0; a < 2; ++a)
; #pragma unroll
;             for (int b = 0; b < 2; ++b)
; #pragma unroll
;                 for (int m = 0; m < 4; ++m)
; #pragma unroll
;                     for (int n = 0; n < 2; ++n) acc[a][b][m][n] = (f32x4){0.f, 0.f, 0.f, 0.f};
;         cur = nxt; cA = nA; cB = nB; ++ui;
;         if constexpr (ALIGN_EPI) { if (wr == 1) PG8_BAR; }
	v_pk_add_f32 v[36:37], v[42:43], v[46:47]
	v_pk_add_f32 v[38:39], v[40:41], v[44:45]
	v_pk_add_f32 v[34:35], v[34:35], v[36:37]
	v_pk_add_f32 v[32:33], v[32:33], v[38:39]
	s_nop 0
	v_pk_mov_b32 v[36:37], v[32:33], v[34:35] op_sel:[1,0]
	v_mov_b32_e32 v33, v35
	v_pk_add_f32 v[32:33], v[36:37], v[32:33]
	v_lshl_add_u64 v[34:35], s[12:13], 0, v[52:53]
	v_add_f32_e32 v32, v32, v33
	v_fmamk_f32 v32, v32, 0x3a800000, v170
	v_mul_f32_e32 v33, 0x4b800000, v32
	v_cmp_gt_f32_e32 vcc, s62, v32
	s_nop 1
	v_cndmask_b32_e32 v32, v32, v33, vcc
	v_rsq_f32_e32 v36, v32
	v_lshl_add_u64 v[32:33], s[54:55], 0, v[50:51]
	v_lshl_add_u64 v[32:33], v[32:33], 0, v[160:161]
	v_mul_f32_e32 v37, 0x45800000, v36
	v_cndmask_b32_e32 v36, v36, v37, vcc
	v_pk_fma_f32 v[30:31], v[30:31], v[36:37], v[110:111] op_sel_hi:[1,0,1]
	v_pk_fma_f32 v[28:29], v[28:29], v[36:37], v[108:109] op_sel_hi:[1,0,1]
	v_pk_fma_f32 v[26:27], v[26:27], v[36:37], v[106:107] op_sel_hi:[1,0,1]
	v_pk_fma_f32 v[24:25], v[24:25], v[36:37], v[104:105] op_sel_hi:[1,0,1]
	v_pk_fma_f32 v[22:23], v[22:23], v[36:37], v[102:103] op_sel_hi:[1,0,1]
	v_pk_fma_f32 v[20:21], v[20:21], v[36:37], v[100:101] op_sel_hi:[1,0,1]
	v_pk_fma_f32 v[18:19], v[18:19], v[36:37], v[98:99] op_sel_hi:[1,0,1]
	v_pk_fma_f32 v[16:17], v[16:17], v[36:37], v[96:97] op_sel_hi:[1,0,1]
	v_cvt_f16_f32_e32 v28, v28
	v_cvt_f16_f32_sdwa v29, v29 dst_sel:WORD_1 dst_unused:UNUSED_PAD src0_sel:DWORD
	v_cvt_f16_f32_e32 v30, v30
	v_cvt_f16_f32_sdwa v31, v31 dst_sel:WORD_1 dst_unused:UNUSED_PAD src0_sel:DWORD
	v_cvt_f16_f32_e32 v24, v24
	v_cvt_f16_f32_sdwa v25, v25 dst_sel:WORD_1 dst_unused:UNUSED_PAD src0_sel:DWORD
	v_cvt_f16_f32_e32 v26, v26
	v_cvt_f16_f32_sdwa v27, v27 dst_sel:WORD_1 dst_unused:UNUSED_PAD src0_sel:DWORD
	v_cvt_f16_f32_e32 v20, v20
	v_cvt_f16_f32_sdwa v21, v21 dst_sel:WORD_1 dst_unused:UNUSED_PAD src0_sel:DWORD
	v_cvt_f16_f32_e32 v22, v22
	v_cvt_f16_f32_sdwa v23, v23 dst_sel:WORD_1 dst_unused:UNUSED_PAD src0_sel:DWORD
	v_cvt_f16_f32_e32 v36, v16
	v_cvt_f16_f32_sdwa v37, v17 dst_sel:WORD_1 dst_unused:UNUSED_PAD src0_sel:DWORD
	v_cvt_f16_f32_e32 v38, v18
	v_cvt_f16_f32_sdwa v39, v19 dst_sel:WORD_1 dst_unused:UNUSED_PAD src0_sel:DWORD
	v_or_b32_e32 v16, v29, v28
	v_or_b32_e32 v17, v31, v30
	v_or_b32_e32 v18, v25, v24
	v_or_b32_e32 v19, v27, v26
	v_or_b32_e32 v20, v21, v20
	v_or_b32_e32 v21, v23, v22
	v_or_b32_e32 v22, v37, v36
	v_or_b32_e32 v23, v39, v38
	global_store_dwordx4 v[32:33], v[16:19], off sc1
	global_store_dwordx4 v[32:33], v[20:23], off offset:256 sc1
	global_load_dwordx4 v[16:19], v[34:35], off
	s_nop 0
	global_load_dwordx4 v[20:23], v[34:35], off offset:16
	global_load_dwordx4 v[24:27], v[34:35], off offset:32
	global_load_dwordx4 v[28:31], v[34:35], off offset:48
	v_lshlrev_b64 v[32:33], 12, v[48:49]
	s_andn2_b64 vcc, exec, s[6:7]
	s_waitcnt vmcnt(2)
	v_pk_add_f32 v[18:19], v[18:19], v[22:23]
	v_pk_add_f32 v[16:17], v[16:17], v[20:21]
	s_waitcnt vmcnt(0)
	v_pk_add_f32 v[20:21], v[26:27], v[30:31]
	v_pk_add_f32 v[22:23], v[24:25], v[28:29]
	v_pk_add_f32 v[18:19], v[18:19], v[20:21]
	v_pk_add_f32 v[16:17], v[16:17], v[22:23]
	s_nop 0
	v_pk_mov_b32 v[20:21], v[16:17], v[18:19] op_sel:[1,0]
	v_mov_b32_e32 v17, v19
	v_pk_add_f32 v[16:17], v[20:21], v[16:17]
	s_nop 0
	v_add_f32_e32 v16, v16, v17
	v_fmamk_f32 v16, v16, 0x3a800000, v170
	v_mul_f32_e32 v17, 0x4b800000, v16
	v_cmp_gt_f32_e64 s[0:1], s62, v16
	s_nop 1
	v_cndmask_b32_e64 v16, v16, v17, s[0:1]
	v_rsq_f32_e32 v18, v16
	v_lshl_add_u64 v[16:17], s[54:55], 0, v[32:33]
	v_lshl_add_u64 v[16:17], v[16:17], 0, v[160:161]
	v_mul_f32_e32 v19, 0x45800000, v18
	v_cndmask_b32_e64 v18, v18, v19, s[0:1]
	v_pk_fma_f32 v[14:15], v[14:15], v[18:19], v[110:111] op_sel_hi:[1,0,1]
	v_pk_fma_f32 v[12:13], v[12:13], v[18:19], v[108:109] op_sel_hi:[1,0,1]
	v_pk_fma_f32 v[10:11], v[10:11], v[18:19], v[106:107] op_sel_hi:[1,0,1]
	v_pk_fma_f32 v[8:9], v[8:9], v[18:19], v[104:105] op_sel_hi:[1,0,1]
	v_pk_fma_f32 v[6:7], v[6:7], v[18:19], v[102:103] op_sel_hi:[1,0,1]
	v_pk_fma_f32 v[4:5], v[4:5], v[18:19], v[100:101] op_sel_hi:[1,0,1]
	v_pk_fma_f32 v[2:3], v[2:3], v[18:19], v[98:99] op_sel_hi:[1,0,1]
	v_pk_fma_f32 v[0:1], v[0:1], v[18:19], v[96:97] op_sel_hi:[1,0,1]
	v_cvt_f16_f32_e32 v12, v12
	v_cvt_f16_f32_sdwa v13, v13 dst_sel:WORD_1 dst_unused:UNUSED_PAD src0_sel:DWORD
	v_cvt_f16_f32_e32 v14, v14
	v_cvt_f16_f32_sdwa v15, v15 dst_sel:WORD_1 dst_unused:UNUSED_PAD src0_sel:DWORD
	v_cvt_f16_f32_e32 v8, v8
	v_cvt_f16_f32_sdwa v9, v9 dst_sel:WORD_1 dst_unused:UNUSED_PAD src0_sel:DWORD
	v_cvt_f16_f32_e32 v10, v10
	v_cvt_f16_f32_sdwa v11, v11 dst_sel:WORD_1 dst_unused:UNUSED_PAD src0_sel:DWORD
	v_cvt_f16_f32_e32 v4, v4
	v_cvt_f16_f32_sdwa v5, v5 dst_sel:WORD_1 dst_unused:UNUSED_PAD src0_sel:DWORD
	v_cvt_f16_f32_e32 v6, v6
	v_cvt_f16_f32_sdwa v7, v7 dst_sel:WORD_1 dst_unused:UNUSED_PAD src0_sel:DWORD
	v_cvt_f16_f32_e32 v18, v0
	v_cvt_f16_f32_sdwa v19, v1 dst_sel:WORD_1 dst_unused:UNUSED_PAD src0_sel:DWORD
	v_cvt_f16_f32_e32 v20, v2
	v_cvt_f16_f32_sdwa v21, v3 dst_sel:WORD_1 dst_unused:UNUSED_PAD src0_sel:DWORD
	v_or_b32_e32 v0, v13, v12
	v_or_b32_e32 v1, v15, v14
	v_or_b32_e32 v2, v9, v8
	v_or_b32_e32 v3, v11, v10
	s_mov_b64 s[0:1], -1
	v_or_b32_e32 v4, v5, v4
	v_or_b32_e32 v5, v7, v6
	v_or_b32_e32 v6, v19, v18
	v_or_b32_e32 v7, v21, v20
	global_store_dwordx4 v[16:17], v[0:3], off sc1
	global_store_dwordx4 v[16:17], v[4:7], off offset:256 sc1
	s_cbranch_vccnz .LBB0_629
	s_andn2_b64 vcc, exec, s[8:9]
	s_cbranch_vccnz .LBB0_628
	s_barrier
	s_branch .LBB0_628
